# C item load issue order: xhat rows first, then mixing-matrix fragments, then gate prefetch (fragment address pairs moved to v52-59); waits recounted
# baseline (speedup 1.0000x reference)
.LBB0_779:
	v_mov_b32_e32 v43, v0
	s_ashr_i32 s5, s3, 31
	v_ashrrev_i32_e32 v44, 7, v43
	s_waitcnt vmcnt(2)
	v_add_u32_e32 v164, s2, v44
	v_ashrrev_i32_e32 v165, 31, v164
	v_and_b32_e32 v168, 31, v43
	s_waitcnt vmcnt(0)
	v_lshlrev_b64 v[2:3], 15, v[164:165]
	v_bfe_u32 v169, v43, 5, 1
	v_lshl_add_u64 v[2:3], s[56:57], 0, v[2:3]
	v_lshlrev_b32_e32 v154, 8, v168
	v_lshl_add_u64 v[2:3], v[2:3], 0, v[154:155]
	v_lshlrev_b32_e32 v154, 4, v169
	v_ashrrev_i32_e32 v45, 2, v43
	v_add_u32_e32 v18, s3, v45
	v_ashrrev_i32_e32 v19, 31, v18
	v_lshlrev_b32_e32 v20, 6, v43
	v_lshlrev_b64 v[18:19], 12, v[18:19]
	v_and_b32_e32 v46, 0xc0, v20
	v_lshl_add_u64 v[18:19], s[60:61], 0, v[18:19]
	v_lshlrev_b32_e32 v20, 1, v46
	v_mov_b32_e32 v21, v155
	v_lshl_add_u64 v[34:35], v[18:19], 0, v[20:21]
	global_load_dwordx4 v[18:21], v[34:35], off offset:3632
	global_load_dwordx4 v[22:25], v[34:35], off offset:3616
	global_load_dwordx4 v[26:29], v[34:35], off offset:3600
	global_load_dwordx4 v[30:33], v[34:35], off offset:3584
	global_load_dwordx4 v[36:39], v[34:35], off offset:3680
	global_load_dwordx4 v[202:205], v[34:35], off offset:3664
	global_load_dwordx4 v[48:51], v[34:35], off offset:3648
	global_load_dwordx4 v[206:209], v[34:35], off offset:3696
	v_lshl_add_u64 v[52:53], v[2:3], 0, v[154:155]
	v_add_co_u32_e32 v54, vcc, s14, v52
	s_nop 0
	v_addc_co_u32_e32 v55, vcc, 0, v53, vcc
	v_add_co_u32_e32 v56, vcc, s17, v52
	global_load_dwordx4 v[2:5], v[52:53], off
	global_load_dwordx4 v[6:9], v[54:55], off
	v_addc_co_u32_e32 v57, vcc, 0, v53, vcc
	v_add_co_u32_e32 v58, vcc, s30, v52
	global_load_dwordx4 v[10:13], v[56:57], off
	s_nop 0
	v_addc_co_u32_e32 v59, vcc, 0, v53, vcc
	global_load_dwordx4 v[14:17], v[58:59], off
	global_load_dwordx4 v[138:141], v[52:53], off offset:32
	global_load_dwordx4 v[142:145], v[54:55], off offset:32
	global_load_dwordx4 v[146:149], v[56:57], off offset:32
	global_load_dwordx4 v[150:153], v[58:59], off offset:32
	global_load_dwordx4 v[126:129], v[54:55], off offset:64
	global_load_dwordx4 v[130:133], v[56:57], off offset:64
	global_load_dwordx4 v[134:137], v[58:59], off offset:64
	global_load_dwordx4 v[114:117], v[54:55], off offset:96
	global_load_dwordx4 v[118:121], v[56:57], off offset:96
	global_load_dwordx4 v[122:125], v[58:59], off offset:96
	global_load_dwordx4 v[106:109], v[56:57], off offset:128
	global_load_dwordx4 v[110:113], v[58:59], off offset:128
	global_load_dwordx4 v[98:101], v[56:57], off offset:160
	global_load_dwordx4 v[102:105], v[58:59], off offset:160
	global_load_dwordx4 v[94:97], v[58:59], off offset:192
	global_load_dwordx4 v[90:93], v[58:59], off offset:224
	v_and_b32_e32 v215, 31, v0
	v_add_u32_e32 v215, s3, v215
	v_lshlrev_b32_e32 v215, 12, v215
	v_and_b32_e32 v245, 0x1c0, v0
	v_add_u32_e32 v215, v215, v245
	v_bfe_u32 v245, v0, 5, 1
	v_lshl_add_u32 v215, v245, 3, v215
	global_load_dwordx2 v[216:217], v215, s[60:61] offset:3072
	global_load_dwordx2 v[218:219], v215, s[60:61] offset:3088
	global_load_dwordx2 v[220:221], v215, s[60:61] offset:3104
	global_load_dwordx2 v[222:223], v215, s[60:61] offset:3120
	s_add_u32 s98, s60, 0x20000
	s_addc_u32 s99, s61, 0
	global_load_dwordx2 v[224:225], v215, s[98:99] offset:3072
	global_load_dwordx2 v[226:227], v215, s[98:99] offset:3088
	global_load_dwordx2 v[228:229], v215, s[98:99] offset:3104
	global_load_dwordx2 v[230:231], v215, s[98:99] offset:3120
	s_add_u32 s100, s60, 0x40000
	s_addc_u32 s101, s61, 0
	global_load_dwordx2 v[232:233], v215, s[100:101] offset:3072
	global_load_dwordx2 v[234:235], v215, s[100:101] offset:3088
	global_load_dwordx2 v[236:237], v215, s[100:101] offset:3104
	global_load_dwordx2 v[238:239], v215, s[100:101] offset:3120
	s_add_u32 s98, s60, 0x60000
	s_addc_u32 s99, s61, 0
	global_load_dwordx2 v[240:241], v215, s[98:99] offset:3072
	global_load_dwordx2 v[246:247], v215, s[98:99] offset:3088
	global_load_dwordx2 v[252:253], v215, s[98:99] offset:3104
	global_load_dwordx2 v[254:255], v215, s[98:99] offset:3120
	v_lshrrev_b32_e32 v42, 5, v43
	s_add_i32 s4, s4, s46
	s_waitcnt vmcnt(43)
	v_lshlrev_b32_e32 v178, 16, v18
	s_waitcnt vmcnt(42)
	v_lshlrev_b32_e32 v186, 16, v22
	s_waitcnt vmcnt(41)
	v_lshlrev_b32_e32 v194, 16, v26
	s_waitcnt vmcnt(40)
	v_lshlrev_b32_e32 v200, 16, v30
	v_and_b32_e32 v199, 0xffff0000, v30
	v_add_f32_e32 v30, 0, v200
	v_lshlrev_b32_e32 v198, 16, v31
	v_add_f32_e32 v30, v30, v199
	v_and_b32_e32 v197, 0xffff0000, v31
	v_mul_f32_e32 v31, v199, v199
	v_add_f32_e32 v30, v30, v198
	v_lshlrev_b32_e32 v196, 16, v32
	v_fmac_f32_e32 v31, v200, v200
	v_add_f32_e32 v30, v30, v197
	v_and_b32_e32 v195, 0xffff0000, v32
	v_fmac_f32_e32 v31, v198, v198
	v_add_f32_e32 v30, v30, v196
	v_lshlrev_b32_e32 v193, 16, v33
	v_fmac_f32_e32 v31, v197, v197
	v_add_f32_e32 v30, v30, v195
	v_and_b32_e32 v191, 0xffff0000, v33
	v_fmac_f32_e32 v31, v196, v196
	v_add_f32_e32 v30, v30, v193
	v_fmac_f32_e32 v31, v195, v195
	v_add_f32_e32 v30, v30, v191
	v_fmac_f32_e32 v31, v193, v193
	v_and_b32_e32 v192, 0xffff0000, v26
	v_add_f32_e32 v26, v30, v194
	v_fmac_f32_e32 v31, v191, v191
	v_lshlrev_b32_e32 v190, 16, v27
	v_add_f32_e32 v26, v26, v192
	v_and_b32_e32 v189, 0xffff0000, v27
	v_fmac_f32_e32 v31, v194, v194
	v_add_f32_e32 v26, v26, v190
	v_lshlrev_b32_e32 v188, 16, v28
	v_fmac_f32_e32 v31, v192, v192
	v_add_f32_e32 v26, v26, v189
	v_and_b32_e32 v187, 0xffff0000, v28
	v_fmac_f32_e32 v31, v190, v190
	v_add_f32_e32 v26, v26, v188
	v_lshlrev_b32_e32 v184, 16, v29
	v_fmac_f32_e32 v31, v189, v189
	v_add_f32_e32 v26, v26, v187
	v_and_b32_e32 v182, 0xffff0000, v29
	v_fmac_f32_e32 v31, v188, v188
	v_add_f32_e32 v26, v26, v184
	v_fmac_f32_e32 v31, v187, v187
	v_add_f32_e32 v26, v26, v182
	v_fmac_f32_e32 v31, v184, v184
	v_and_b32_e32 v185, 0xffff0000, v22
	v_add_f32_e32 v22, v26, v186
	v_fmac_f32_e32 v31, v182, v182
	v_lshlrev_b32_e32 v183, 16, v23
	v_add_f32_e32 v22, v22, v185
	v_and_b32_e32 v179, 0xffff0000, v23
	v_fmac_f32_e32 v31, v186, v186
	v_add_f32_e32 v22, v22, v183
	v_lshlrev_b32_e32 v177, 16, v24
	v_fmac_f32_e32 v31, v185, v185
	v_add_f32_e32 v22, v22, v179
	v_and_b32_e32 v175, 0xffff0000, v24
	v_fmac_f32_e32 v31, v183, v183
	v_add_f32_e32 v22, v22, v177
	v_lshlrev_b32_e32 v173, 16, v25
	v_fmac_f32_e32 v31, v179, v179
	v_add_f32_e32 v22, v22, v175
	v_and_b32_e32 v171, 0xffff0000, v25
	v_fmac_f32_e32 v31, v177, v177
	v_add_f32_e32 v22, v22, v173
	v_fmac_f32_e32 v31, v175, v175
	v_add_f32_e32 v22, v22, v171
	v_fmac_f32_e32 v31, v173, v173
	v_and_b32_e32 v176, 0xffff0000, v18
	v_add_f32_e32 v18, v22, v178
	v_fmac_f32_e32 v31, v171, v171
	v_lshlrev_b32_e32 v174, 16, v19
	v_add_f32_e32 v18, v18, v176
	v_and_b32_e32 v172, 0xffff0000, v19
	v_fmac_f32_e32 v31, v178, v178
	v_add_f32_e32 v18, v18, v174
	v_lshlrev_b32_e32 v167, 16, v20
	v_fmac_f32_e32 v31, v176, v176
	v_add_f32_e32 v18, v18, v172
	v_and_b32_e32 v165, 0xffff0000, v20
	v_fmac_f32_e32 v31, v174, v174
	v_add_f32_e32 v18, v18, v167
	v_lshlrev_b32_e32 v64, 16, v21
	v_fmac_f32_e32 v31, v172, v172
	v_add_f32_e32 v18, v18, v165
	v_and_b32_e32 v62, 0xffff0000, v21
	v_fmac_f32_e32 v31, v167, v167
	v_add_f32_e32 v18, v18, v64
	v_fmac_f32_e32 v31, v165, v165
	v_add_f32_e32 v18, v18, v62
	s_waitcnt vmcnt(37)
	v_lshlrev_b32_e32 v170, 16, v48
	v_fmac_f32_e32 v31, v64, v64
	v_and_b32_e32 v166, 0xffff0000, v48
	v_add_f32_e32 v18, v18, v170
	v_fmac_f32_e32 v31, v62, v62
	v_lshlrev_b32_e32 v65, 16, v49
	v_add_f32_e32 v18, v18, v166
	v_and_b32_e32 v63, 0xffff0000, v49
	v_fmac_f32_e32 v31, v170, v170
	v_add_f32_e32 v18, v18, v65
	v_lshlrev_b32_e32 v60, 16, v50
	v_fmac_f32_e32 v31, v166, v166
	v_add_f32_e32 v18, v18, v63
	v_and_b32_e32 v59, 0xffff0000, v50
	v_fmac_f32_e32 v31, v65, v65
	v_add_f32_e32 v18, v18, v60
	v_lshlrev_b32_e32 v57, 16, v51
	v_fmac_f32_e32 v31, v63, v63
	v_add_f32_e32 v18, v18, v59
	v_and_b32_e32 v55, 0xffff0000, v51
	v_fmac_f32_e32 v31, v60, v60
	v_add_f32_e32 v18, v18, v57
	v_fmac_f32_e32 v31, v59, v59
	v_add_f32_e32 v18, v18, v55
	v_lshlrev_b32_e32 v61, 16, v202
	v_fmac_f32_e32 v31, v57, v57
	v_and_b32_e32 v58, 0xffff0000, v202
	v_add_f32_e32 v18, v18, v61
	v_fmac_f32_e32 v31, v55, v55
	v_lshlrev_b32_e32 v56, 16, v203
	v_add_f32_e32 v18, v18, v58
	v_and_b32_e32 v54, 0xffff0000, v203
	v_fmac_f32_e32 v31, v61, v61
	v_add_f32_e32 v18, v18, v56
	v_lshlrev_b32_e32 v53, 16, v204
	v_fmac_f32_e32 v31, v58, v58
	v_add_f32_e32 v18, v18, v54
	v_and_b32_e32 v51, 0xffff0000, v204
	v_fmac_f32_e32 v31, v56, v56
	v_add_f32_e32 v18, v18, v53
	v_lshlrev_b32_e32 v49, 16, v205
	v_fmac_f32_e32 v31, v54, v54
	v_add_f32_e32 v18, v18, v51
	v_and_b32_e32 v47, 0xffff0000, v205
	v_fmac_f32_e32 v31, v53, v53
	v_add_f32_e32 v18, v18, v49
	v_fmac_f32_e32 v31, v51, v51
	v_add_f32_e32 v18, v18, v47
	v_lshlrev_b32_e32 v52, 16, v36
	v_fmac_f32_e32 v31, v49, v49
	v_and_b32_e32 v50, 0xffff0000, v36
	v_add_f32_e32 v18, v18, v52
	v_fmac_f32_e32 v31, v47, v47
	v_lshlrev_b32_e32 v48, 16, v37
	v_add_f32_e32 v18, v18, v50
	v_fmac_f32_e32 v31, v52, v52
	v_add_f32_e32 v18, v18, v48
	v_and_b32_e32 v37, 0xffff0000, v37
	v_fmac_f32_e32 v31, v50, v50
	v_lshlrev_b32_e32 v34, 16, v38
	v_mov_b32_e32 v35, v37
	v_add_f32_e32 v20, v18, v37
	v_fmac_f32_e32 v31, v48, v48
	v_and_b32_e32 v24, 0xffff0000, v38
	v_pk_mul_f32 v[18:19], v[34:35], v[34:35]
	v_add_f32_e32 v20, v20, v34
	v_lshlrev_b32_e32 v25, 16, v39
	v_add_f32_e32 v19, v19, v31
	v_add_f32_e32 v20, v20, v24
	v_add_f32_e32 v21, v18, v19
	v_pk_mul_f32 v[18:19], v[24:25], v[24:25]
	v_add_f32_e32 v20, v20, v25
	v_and_b32_e32 v33, 0xffff0000, v39
	v_add_f32_e32 v18, v18, v21
	s_waitcnt vmcnt(36)
	v_lshlrev_b32_e32 v28, 16, v206
	v_mov_b32_e32 v29, v33
	v_add_f32_e32 v20, v20, v33
	v_add_f32_e32 v21, v19, v18
	v_and_b32_e32 v22, 0xffff0000, v206
	v_pk_mul_f32 v[18:19], v[28:29], v[28:29]
	v_add_f32_e32 v20, v20, v28
	v_lshlrev_b32_e32 v23, 16, v207
	v_add_f32_e32 v19, v19, v21
	v_add_f32_e32 v20, v20, v22
	v_add_f32_e32 v21, v18, v19
	v_pk_mul_f32 v[18:19], v[22:23], v[22:23]
	v_add_f32_e32 v29, v20, v23
	v_and_b32_e32 v31, 0xffff0000, v207
	v_add_f32_e32 v18, v18, v21
	v_lshlrev_b32_e32 v26, 16, v208
	v_mov_b32_e32 v27, v31
	v_add_f32_e32 v29, v29, v31
	v_and_b32_e32 v36, s0, v38
	v_add_f32_e32 v18, v19, v18
	v_and_b32_e32 v20, 0xffff0000, v208
	v_pk_mul_f32 v[38:39], v[26:27], v[26:27]
	v_add_f32_e32 v27, v29, v26
	v_lshlrev_b32_e32 v21, 16, v209
	v_add_f32_e32 v18, v39, v18
	v_add_f32_e32 v27, v27, v20
	v_and_b32_e32 v29, 64, v181
	v_add_f32_e32 v18, v38, v18
	v_pk_mul_f32 v[40:41], v[20:21], v[20:21]
	v_add_f32_e32 v39, v27, v21
	v_xor_b32_e32 v27, 1, v181
	v_add_u32_e32 v29, 64, v29
	v_and_b32_e32 v19, 0xffff0000, v209
	v_add_f32_e32 v18, v40, v18
	v_cmp_lt_i32_e32 vcc, v27, v29
	v_add_f32_e32 v18, v41, v18
	v_mul_f32_e32 v38, v19, v19
	v_cndmask_b32_e32 v27, v181, v27, vcc
	v_lshlrev_b32_e32 v27, 2, v27
	v_pk_add_f32 v[38:39], v[38:39], v[18:19]
	ds_bpermute_b32 v41, v27, v39
	ds_bpermute_b32 v40, v27, v38
	v_xor_b32_e32 v35, 2, v181
	v_cmp_lt_i32_e32 vcc, v35, v29
	v_and_b32_e32 v30, s0, v206
	v_mov_b32_e32 v32, v36
	v_cndmask_b32_e32 v29, v181, v35, vcc
	v_lshlrev_b32_e32 v29, 2, v29
	s_waitcnt lgkmcnt(0)
	v_pk_add_f32 v[38:39], v[38:39], v[40:41]
	ds_bpermute_b32 v41, v29, v39
	ds_bpermute_b32 v40, v29, v38
	s_waitcnt lgkmcnt(0)
	v_pk_add_f32 v[40:41], v[38:39], v[40:41]
	s_nop 0
	v_pk_mul_f32 v[38:39], v[40:41], s[22:23] op_sel_hi:[1,0]
	v_pk_fma_f32 v[36:37], v[40:41], s[22:23], v[36:37] op_sel_hi:[1,0,1] neg_lo:[1,0,0] neg_hi:[1,0,0]
	v_fma_f32 v18, -v39, v39, v38
	v_max_f32_e32 v18, 0, v18
	v_add_f32_e32 v18, 0x358637bd, v18
	v_cmp_gt_f32_e32 vcc, s33, v18
	v_mul_f32_e32 v27, 0x4b800000, v18
	v_sub_f32_e32 v29, v200, v39
	v_cndmask_b32_e32 v18, v18, v27, vcc
	v_rsq_f32_e32 v18, v18
	v_sub_f32_e32 v19, v19, v39
	v_mul_f32_e32 v27, 0x45800000, v18
	v_cndmask_b32_e32 v18, v18, v27, vcc
	v_mul_f32_e32 v29, v29, v18
	v_lshlrev_b32_e32 v27, 1, v45
	v_bfe_u32 v35, v29, 16, 1
	v_ashrrev_i32_e32 v45, 1, v43
	v_and_b32_e32 v27, 14, v27
	v_add3_u32 v29, v29, v35, s15
	v_lshl_add_u32 v35, v46, 8, 32
	v_and_b32_e32 v46, -16, v45
	v_add3_u32 v200, v35, v46, v27
	ds_write_b16_d16_hi v200, v29 offset:55296
	v_mul_f32_e64 v215, -v39, v18
	v_fma_f32 v29, v199, v18, v215
	v_cvt_pk_bf16_f32 v29, v29, v29
	v_bitop3_b32 v199, v45, 16, -16 bitop3:0x6c
	v_add3_u32 v201, v35, v199, v27
	ds_write_b16 v201, v29 offset:55552
	v_fma_f32 v29, v198, v18, v215
	v_cvt_pk_bf16_f32 v29, v29, v29
	v_bitop3_b32 v198, v45, 32, -16 bitop3:0x6c
	v_add3_u32 v202, v35, v198, v27
	ds_write_b16 v202, v29 offset:55808
	v_fma_f32 v29, v197, v18, v215
	v_cvt_pk_bf16_f32 v29, v29, v29
	v_bitop3_b32 v197, v45, 48, -16 bitop3:0x6c
	v_add3_u32 v203, v35, v197, v27
	ds_write_b16 v203, v29 offset:56064
	v_fma_f32 v29, v196, v18, v215
	v_cvt_pk_bf16_f32 v29, v29, v29
	v_bitop3_b32 v196, v45, 64, -16 bitop3:0x6c
	v_add3_u32 v204, v35, v196, v27
	ds_write_b16 v204, v29 offset:56320
	v_fma_f32 v29, v195, v18, v215
	v_cvt_pk_bf16_f32 v29, v29, v29
	v_bitop3_b32 v195, v45, s34, -16 bitop3:0x6c
	v_add3_u32 v205, v35, v195, v27
	ds_write_b16 v205, v29 offset:56576
	v_fma_f32 v29, v193, v18, v215
	v_cvt_pk_bf16_f32 v29, v29, v29
	v_bitop3_b32 v193, v45, s31, -16 bitop3:0x6c
	v_add3_u32 v206, v35, v193, v27
	ds_write_b16 v206, v29 offset:56832
	v_fma_f32 v29, v191, v18, v215
	v_cvt_pk_bf16_f32 v29, v29, v29
	v_bitop3_b32 v191, v45, s13, -16 bitop3:0x6c
	v_add3_u32 v207, v35, v191, v27
	ds_write_b16 v207, v29 offset:57088
	v_fma_f32 v29, v194, v18, v215
	v_cvt_pk_bf16_f32 v29, v29, v29
	v_bitop3_b32 v194, v45, s12, -16 bitop3:0x6c
	v_add3_u32 v208, v35, v194, v27
	ds_write_b16 v208, v29 offset:57344
	v_fma_f32 v29, v192, v18, v215
	v_cvt_pk_bf16_f32 v29, v29, v29
	v_bitop3_b32 v192, v45, s35, -16 bitop3:0x6c
	v_add3_u32 v209, v35, v192, v27
	ds_write_b16 v209, v29 offset:57600
	v_fma_f32 v29, v190, v18, v215
	v_cvt_pk_bf16_f32 v29, v29, v29
	v_bitop3_b32 v190, v45, s36, -16 bitop3:0x6c
	v_add3_u32 v210, v35, v190, v27
	ds_write_b16 v210, v29 offset:57856
	v_fma_f32 v29, v189, v18, v215
	v_cvt_pk_bf16_f32 v29, v29, v29
	v_bitop3_b32 v189, v45, s37, -16 bitop3:0x6c
	v_add3_u32 v211, v35, v189, v27
	ds_write_b16 v211, v29 offset:58112
	v_fma_f32 v29, v188, v18, v215
	v_cvt_pk_bf16_f32 v29, v29, v29
	v_bitop3_b32 v188, v45, s16, -16 bitop3:0x6c
	v_add3_u32 v212, v35, v188, v27
	ds_write_b16 v212, v29 offset:58368
	v_fma_f32 v29, v187, v18, v215
	v_cvt_pk_bf16_f32 v29, v29, v29
	v_bitop3_b32 v187, v45, s42, -16 bitop3:0x6c
	v_add3_u32 v213, v35, v187, v27
	ds_write_b16 v213, v29 offset:58624
	v_fma_f32 v29, v184, v18, v215
	v_cvt_pk_bf16_f32 v29, v29, v29
	v_bitop3_b32 v184, v45, s43, -16 bitop3:0x6c
	v_add3_u32 v214, v35, v184, v27
	ds_write_b16 v214, v29 offset:58880
	v_sub_f32_e32 v29, v182, v39
	v_mul_f32_e32 v29, v29, v18
	v_bfe_u32 v182, v29, 16, 1
	v_bitop3_b32 v45, v45, s94, -16 bitop3:0x6c
	v_add_u32_e32 v38, 0xd800, v35
	v_add3_u32 v29, v29, v182, s15
	v_add3_u32 v35, v35, v45, v27
	ds_write_b16_d16_hi v35, v29 offset:59136
	v_fma_f32 v29, v186, v18, v215
	v_cvt_pk_bf16_f32 v29, v29, v29
	ds_write_b16 v200, v29 offset:59392
	v_fma_f32 v29, v185, v18, v215
	v_cvt_pk_bf16_f32 v29, v29, v29
	ds_write_b16 v201, v29 offset:59648
	v_fma_f32 v29, v183, v18, v215
	v_cvt_pk_bf16_f32 v29, v29, v29
	ds_write_b16 v202, v29 offset:59904
	v_fma_f32 v29, v179, v18, v215
	v_cvt_pk_bf16_f32 v29, v29, v29
	ds_write_b16 v203, v29 offset:60160
	v_fma_f32 v29, v177, v18, v215
	v_cvt_pk_bf16_f32 v29, v29, v29
	ds_write_b16 v204, v29 offset:60416
	v_fma_f32 v29, v175, v18, v215
	v_cvt_pk_bf16_f32 v29, v29, v29
	ds_write_b16 v205, v29 offset:60672
	v_fma_f32 v29, v173, v18, v215
	v_cvt_pk_bf16_f32 v29, v29, v29
	ds_write_b16 v206, v29 offset:60928
	v_fma_f32 v29, v171, v18, v215
	v_cvt_pk_bf16_f32 v29, v29, v29
	ds_write_b16 v207, v29 offset:61184
	v_fma_f32 v29, v178, v18, v215
	v_cvt_pk_bf16_f32 v29, v29, v29
	ds_write_b16 v208, v29 offset:61440
	v_fma_f32 v29, v176, v18, v215
	v_cvt_pk_bf16_f32 v29, v29, v29
	ds_write_b16 v209, v29 offset:61696
	v_fma_f32 v29, v174, v18, v215
	v_cvt_pk_bf16_f32 v29, v29, v29
	ds_write_b16 v210, v29 offset:61952
	v_fma_f32 v29, v172, v18, v215
	v_cvt_pk_bf16_f32 v29, v29, v29
	ds_write_b16 v211, v29 offset:62208
	v_fma_f32 v29, v167, v18, v215
	v_cvt_pk_bf16_f32 v29, v29, v29
	ds_write_b16 v212, v29 offset:62464
	v_fma_f32 v29, v165, v18, v215
	v_cvt_pk_bf16_f32 v29, v29, v29
	ds_write_b16 v213, v29 offset:62720
	v_fma_f32 v29, v64, v18, v215
	v_cvt_pk_bf16_f32 v29, v29, v29
	ds_write_b16 v214, v29 offset:62976
	v_fma_f32 v29, v62, v18, v215
	v_cvt_pk_bf16_f32 v29, v29, v29
	ds_write_b16 v35, v29 offset:63232
	v_fma_f32 v29, v170, v18, v215
	v_cvt_pk_bf16_f32 v29, v29, v29
	ds_write_b16 v200, v29 offset:63488
	v_fma_f32 v29, v166, v18, v215
	v_cvt_pk_bf16_f32 v29, v29, v29
	ds_write_b16 v201, v29 offset:63744
	v_fma_f32 v29, v65, v18, v215
	v_cvt_pk_bf16_f32 v29, v29, v29
	ds_write_b16 v202, v29 offset:64000
	v_fma_f32 v29, v63, v18, v215
	v_cvt_pk_bf16_f32 v29, v29, v29
	ds_write_b16 v203, v29 offset:64256
	v_fma_f32 v29, v60, v18, v215
	v_cvt_pk_bf16_f32 v29, v29, v29
	ds_write_b16 v204, v29 offset:64512
	v_fma_f32 v29, v59, v18, v215
	v_cvt_pk_bf16_f32 v29, v29, v29
	ds_write_b16 v205, v29 offset:64768
	v_fma_f32 v29, v57, v18, v215
	v_cvt_pk_bf16_f32 v29, v29, v29
	ds_write_b16 v206, v29 offset:65024
	v_fma_f32 v29, v55, v18, v215
	v_cvt_pk_bf16_f32 v29, v29, v29
	ds_write_b16 v207, v29 offset:65280
	v_fma_f32 v29, v61, v18, v215
	v_cvt_pk_bf16_f32 v29, v29, v29
	v_add3_u32 v35, v38, v194, v27
	ds_write_b16 v35, v29 offset:10240
	v_fma_f32 v29, v58, v18, v215
	v_cvt_pk_bf16_f32 v29, v29, v29
	v_add3_u32 v55, v38, v192, v27
	ds_write_b16 v55, v29 offset:10496
	v_fma_f32 v29, v56, v18, v215
	v_cvt_pk_bf16_f32 v29, v29, v29
	v_add3_u32 v56, v38, v190, v27
	ds_write_b16 v56, v29 offset:10752
	v_fma_f32 v29, v54, v18, v215
	v_cvt_pk_bf16_f32 v29, v29, v29
	v_add3_u32 v54, v38, v189, v27
	ds_write_b16 v54, v29 offset:11008
	v_fma_f32 v29, v53, v18, v215
	v_cvt_pk_bf16_f32 v29, v29, v29
	v_add3_u32 v53, v38, v188, v27
	ds_write_b16 v53, v29 offset:11264
	v_fma_f32 v29, v51, v18, v215
	v_cvt_pk_bf16_f32 v29, v29, v29
	v_add3_u32 v51, v38, v187, v27
	ds_write_b16 v51, v29 offset:11520
	v_fma_f32 v29, v49, v18, v215
	v_cvt_pk_bf16_f32 v29, v29, v29
	v_add3_u32 v49, v38, v184, v27
	ds_write_b16 v49, v29 offset:11776
	v_fma_f32 v29, v47, v18, v215
	v_cvt_pk_bf16_f32 v29, v29, v29
	v_add3_u32 v45, v38, v45, v27
	ds_write_b16 v45, v29 offset:12032
	v_fma_f32 v29, v52, v18, v215
	v_cvt_pk_bf16_f32 v29, v29, v29
	v_add3_u32 v46, v38, v46, v27
	ds_write_b16 v46, v29 offset:12288
	v_fma_f32 v29, v50, v18, v215
	v_cvt_pk_bf16_f32 v29, v29, v29
	v_add3_u32 v46, v38, v199, v27
	ds_write_b16 v46, v29 offset:12544
	v_fma_f32 v29, v48, v18, v215
	v_cvt_pk_bf16_f32 v29, v29, v29
	v_add3_u32 v46, v38, v198, v27
	ds_write_b16 v46, v29 offset:12800
	v_mul_f32_e32 v29, v37, v18
	v_bfe_u32 v36, v29, 16, 1
	v_add3_u32 v29, v29, v36, s15
	v_add3_u32 v36, v38, v197, v27
	ds_write_b16_d16_hi v36, v29 offset:13056
	v_fma_f32 v29, v34, v18, v215
	v_cvt_pk_bf16_f32 v29, v29, v29
	v_add3_u32 v34, v38, v196, v27
	ds_write_b16 v34, v29 offset:13312
	v_sub_f32_e32 v29, v24, v39
	v_pk_fma_f32 v[24:25], v[40:41], s[22:23], v[24:25] op_sel_hi:[1,0,1] neg_lo:[1,0,0] neg_hi:[1,0,0]
	v_mul_f32_e32 v29, v29, v18
	v_mul_f32_e32 v24, v25, v18
	v_bfe_u32 v34, v29, 16, 1
	v_bfe_u32 v25, v24, 16, 1
	v_add3_u32 v29, v29, v34, s15
	v_add3_u32 v34, v38, v195, v27
	v_add3_u32 v24, v24, v25, s15
	v_add3_u32 v25, v38, v193, v27
	ds_write_b16_d16_hi v34, v29 offset:13568
	ds_write_b16_d16_hi v25, v24 offset:13824
	v_pk_fma_f32 v[24:25], v[40:41], s[22:23], v[32:33] op_sel_hi:[1,0,1] neg_lo:[1,0,0] neg_hi:[1,0,0]
	v_and_b32_e32 v167, 15, v43
	v_mul_f32_e32 v24, v25, v18
	v_bfe_u32 v25, v24, 16, 1
	v_add3_u32 v24, v24, v25, s15
	v_add3_u32 v25, v38, v191, v27
	ds_write_b16_d16_hi v25, v24 offset:14080
	v_fma_f32 v24, v28, v18, v215
	v_cvt_pk_bf16_f32 v24, v24, v24
	ds_write_b16 v35, v24 offset:14336
	v_sub_f32_e32 v24, v22, v39
	v_pk_fma_f32 v[22:23], v[40:41], s[22:23], v[22:23] op_sel_hi:[1,0,1] neg_lo:[1,0,0] neg_hi:[1,0,0]
	v_mul_f32_e32 v24, v24, v18
	v_mul_f32_e32 v22, v23, v18
	v_bfe_u32 v25, v24, 16, 1
	v_bfe_u32 v23, v22, 16, 1
	v_add3_u32 v24, v24, v25, s15
	v_add3_u32 v22, v22, v23, s15
	ds_write_b16_d16_hi v55, v24 offset:14592
	ds_write_b16_d16_hi v56, v22 offset:14848
	v_pk_fma_f32 v[22:23], v[40:41], s[22:23], v[30:31] op_sel_hi:[1,0,1] neg_lo:[1,0,0] neg_hi:[1,0,0]
	s_nop 0
	v_mul_f32_e32 v22, v23, v18
	v_bfe_u32 v23, v22, 16, 1
	v_add3_u32 v22, v22, v23, s15
	ds_write_b16_d16_hi v54, v22 offset:15104
	v_fma_f32 v22, v26, v18, v215
	v_cvt_pk_bf16_f32 v22, v22, v22
	ds_write_b16 v53, v22 offset:15360
	v_sub_f32_e32 v22, v20, v39
	v_pk_fma_f32 v[20:21], v[40:41], s[22:23], v[20:21] op_sel_hi:[1,0,1] neg_lo:[1,0,0] neg_hi:[1,0,0]
	v_mul_f32_e32 v22, v22, v18
	v_mul_f32_e32 v20, v21, v18
	v_mul_f32_e32 v18, v19, v18
	v_bfe_u32 v23, v22, 16, 1
	v_bfe_u32 v21, v20, 16, 1
	v_bfe_u32 v19, v18, 16, 1
	v_add3_u32 v22, v22, v23, s15
	v_add3_u32 v20, v20, v21, s15
	v_add3_u32 v18, v18, v19, s15
	ds_write_b16_d16_hi v51, v22 offset:15616
	ds_write_b16_d16_hi v49, v20 offset:15872
	ds_write_b16_d16_hi v45, v18 offset:16128
	v_lshrrev_b32_e32 v18, 1, v43
	v_and_b32_e32 v18, 32, v18
	v_lshl_or_b32 v166, v44, 6, v18
	v_or_b32_e32 v18, v166, v168
	v_lshl_add_u32 v165, v18, 8, 32
	v_bitop3_b32 v18, v42, v167, 1 bitop3:0x6c
	v_lshl_add_u32 v18, v18, 4, v165
	s_waitcnt lgkmcnt(0)
	s_waitcnt vmcnt(16)
	s_barrier
	ds_read_b128 v[170:173], v18 offset:55296
	s_waitcnt lgkmcnt(0)
	v_mfma_f32_32x32x16_bf16 v[50:65], v[170:173], v[2:5], 0
	v_mfma_f32_32x32x16_bf16 v[34:49], v[170:173], v[6:9], 0
	v_mfma_f32_32x32x16_bf16 v[18:33], v[170:173], v[10:13], 0
	v_mfma_f32_32x32x16_bf16 v[2:17], v[170:173], v[14:17], 0
	v_bitop3_b32 v170, v169, v167, 2 bitop3:0x36
	v_lshl_add_u32 v170, v170, 4, v165
	ds_read_b128 v[170:173], v170 offset:55296
	s_waitcnt lgkmcnt(0)
	v_mfma_f32_32x32x16_bf16 v[50:65], v[170:173], v[138:141], v[50:65]
	v_bitop3_b32 v138, v169, v167, 4 bitop3:0x36
	v_lshl_add_u32 v138, v138, 4, v165
	ds_read_b128 v[138:141], v138 offset:55296
	v_mfma_f32_32x32x16_bf16 v[34:49], v[170:173], v[142:145], v[34:49]
	v_mfma_f32_32x32x16_bf16 v[18:33], v[170:173], v[146:149], v[18:33]
	s_waitcnt lgkmcnt(0)
	v_mfma_f32_32x32x16_bf16 v[34:49], v[138:141], v[126:129], v[34:49]
	v_bitop3_b32 v126, v169, v167, 6 bitop3:0x36
	v_lshl_add_u32 v126, v126, 4, v165
	ds_read_b128 v[126:129], v126 offset:55296
	v_mfma_f32_32x32x16_bf16 v[2:17], v[170:173], v[150:153], v[2:17]
	v_mfma_f32_32x32x16_bf16 v[18:33], v[138:141], v[130:133], v[18:33]
	s_waitcnt lgkmcnt(0)
	v_mfma_f32_32x32x16_bf16 v[34:49], v[126:129], v[114:117], v[34:49]
	v_bitop3_b32 v114, v169, v167, 8 bitop3:0x36
	v_lshl_add_u32 v114, v114, 4, v165
	ds_read_b128 v[114:117], v114 offset:55296
	v_mfma_f32_32x32x16_bf16 v[2:17], v[138:141], v[134:137], v[2:17]
	v_mfma_f32_32x32x16_bf16 v[18:33], v[126:129], v[118:121], v[18:33]
	v_mfma_f32_32x32x16_bf16 v[2:17], v[126:129], v[122:125], v[2:17]
	v_lshlrev_b32_e32 v128, 7, v164
	v_or_b32_e32 v126, v128, v168
	v_ashrrev_i32_e32 v127, 31, v126
	v_lshlrev_b64 v[130:131], 2, v[126:127]
	v_lshl_or_b32 v122, v169, 2, v166
	v_or_b32_e32 v124, s3, v168
	v_mov_b32_e32 v125, s5
	s_waitcnt lgkmcnt(0)
	v_mfma_f32_32x32x16_bf16 v[18:33], v[114:117], v[106:109], v[18:33]
	v_bitop3_b32 v106, v169, v167, 10 bitop3:0x36
	v_lshl_add_u32 v106, v106, 4, v165
	ds_read_b128 v[106:109], v106 offset:55296
	v_lshl_add_u64 v[132:133], s[6:7], 0, v[130:131]
	v_lshl_add_u64 v[130:131], s[92:93], 0, v[130:131]
	v_ashrrev_i32_e32 v123, 31, v122
	v_lshlrev_b64 v[122:123], 1, v[122:123]
	v_mfma_f32_32x32x16_bf16 v[2:17], v[114:117], v[110:113], v[2:17]
	s_add_i32 s3, s3, s18
	s_cmpk_gt_i32 s4, 0x7f
	s_waitcnt lgkmcnt(0)
	v_mfma_f32_32x32x16_bf16 v[18:33], v[106:109], v[98:101], v[18:33]
	v_bitop3_b32 v98, v169, v167, 12 bitop3:0x36
	v_lshl_add_u32 v98, v98, 4, v165
	ds_read_b128 v[98:101], v98 offset:55296
	v_mfma_f32_32x32x16_bf16 v[2:17], v[106:109], v[102:105], v[2:17]
	s_waitcnt lgkmcnt(0)
	v_mfma_f32_32x32x16_bf16 v[2:17], v[98:101], v[94:97], v[2:17]
	v_bitop3_b32 v94, v169, v167, 14 bitop3:0x36
	v_lshl_add_u32 v94, v94, 4, v165
	ds_read_b128 v[94:97], v94 offset:55296
	v_ashrrev_i32_e32 v167, 31, v166
	s_waitcnt lgkmcnt(0)
	v_mfma_f32_32x32x16_bf16 v[2:17], v[94:97], v[90:93], v[2:17]
	v_lshlrev_b64 v[90:91], 2, v[166:167]
	v_lshl_add_u64 v[92:93], s[10:11], 0, v[90:91]
	v_lshl_add_u64 v[90:91], s[40:41], 0, v[90:91]
	v_lshl_add_u64 v[92:93], v[92:93], 0, v[154:155]
	v_lshl_add_u64 v[94:95], v[90:91], 0, v[154:155]
	global_load_dwordx4 v[114:117], v[92:93], off
	global_load_dwordx4 v[118:121], v[94:95], off
	global_load_dwordx4 v[106:109], v[92:93], off offset:32
	global_load_dwordx4 v[110:113], v[94:95], off offset:32
	global_load_dwordx4 v[98:101], v[92:93], off offset:64
	global_load_dwordx4 v[102:105], v[94:95], off offset:64
	s_nop 0
	global_load_dwordx4 v[90:93], v[92:93], off offset:96
	s_nop 0
	global_load_dwordx4 v[94:97], v[94:95], off offset:96
	s_nop 0
	global_load_dword v186, v[132:133], off
	global_load_dword v187, v[132:133], off offset:128
	global_load_dword v188, v[132:133], off offset:256
	global_load_dword v189, v[132:133], off offset:384
	global_load_dword v190, v[130:131], off
	global_load_dword v191, v[130:131], off offset:128
	global_load_dword v192, v[130:131], off offset:256
	global_load_dword v193, v[130:131], off offset:384
	v_lshlrev_b64 v[176:177], 11, v[124:125]
	v_lshl_add_u64 v[176:177], s[62:63], 0, v[176:177]
	v_lshl_add_u64 v[176:177], v[176:177], 0, v[122:123]
	v_add_co_u32_e32 v178, vcc, 0x10000, v176
	s_nop 1
	v_addc_co_u32_e32 v179, vcc, 0, v177, vcc
	v_add_co_u32_e32 v182, vcc, 0x20000, v176
	s_nop 1
	v_addc_co_u32_e32 v183, vcc, 0, v177, vcc
	v_add_co_u32_e32 v184, vcc, 0x30000, v176
	s_nop 1
	v_addc_co_u32_e32 v185, vcc, 0, v177, vcc
	s_waitcnt vmcnt(0)
	v_mul_f32_e32 v194, v118, v186
	v_fmac_f32_e32 v194, v50, v114
	v_add_f32_e32 v50, v190, v194
	v_lshlrev_b32_e32 v195, 16, v216
	v_mul_f32_e32 v50, v50, v195
	v_mul_f32_e32 v194, v119, v186
	v_fmac_f32_e32 v194, v51, v115
	v_add_f32_e32 v51, v190, v194
	v_and_b32_e32 v195, 0xffff0000, v216
	v_mul_f32_e32 v51, v51, v195
	v_mul_f32_e32 v194, v120, v186
	v_fmac_f32_e32 v194, v52, v116
	v_add_f32_e32 v52, v190, v194
	v_lshlrev_b32_e32 v195, 16, v217
	v_mul_f32_e32 v52, v52, v195
	v_mul_f32_e32 v194, v121, v186
	v_fmac_f32_e32 v194, v53, v117
	v_add_f32_e32 v53, v190, v194
	v_and_b32_e32 v195, 0xffff0000, v217
	v_mul_f32_e32 v53, v53, v195
	v_cvt_pk_bf16_f32 v50, v50, v51
	v_cvt_pk_bf16_f32 v51, v52, v53
	global_store_dwordx2 v[176:177], v[50:51], off offset:1536
	v_mul_f32_e32 v194, v110, v186
	v_fmac_f32_e32 v194, v54, v106
	v_add_f32_e32 v54, v190, v194
	v_lshlrev_b32_e32 v195, 16, v218
	v_mul_f32_e32 v54, v54, v195
	v_mul_f32_e32 v194, v111, v186
	v_fmac_f32_e32 v194, v55, v107
	v_add_f32_e32 v55, v190, v194
	v_and_b32_e32 v195, 0xffff0000, v218
	v_mul_f32_e32 v55, v55, v195
	v_mul_f32_e32 v194, v112, v186
	v_fmac_f32_e32 v194, v56, v108
	v_add_f32_e32 v56, v190, v194
	v_lshlrev_b32_e32 v195, 16, v219
	v_mul_f32_e32 v56, v56, v195
	v_mul_f32_e32 v194, v113, v186
	v_fmac_f32_e32 v194, v57, v109
	v_add_f32_e32 v57, v190, v194
	v_and_b32_e32 v195, 0xffff0000, v219
	v_mul_f32_e32 v57, v57, v195
	v_cvt_pk_bf16_f32 v54, v54, v55
	v_cvt_pk_bf16_f32 v55, v56, v57
	global_store_dwordx2 v[176:177], v[54:55], off offset:1552
	v_mul_f32_e32 v194, v102, v186
	v_fmac_f32_e32 v194, v58, v98
	v_add_f32_e32 v58, v190, v194
	v_lshlrev_b32_e32 v195, 16, v220
	v_mul_f32_e32 v58, v58, v195
	v_mul_f32_e32 v194, v103, v186
	v_fmac_f32_e32 v194, v59, v99
	v_add_f32_e32 v59, v190, v194
	v_and_b32_e32 v195, 0xffff0000, v220
	v_mul_f32_e32 v59, v59, v195
	v_mul_f32_e32 v194, v104, v186
	v_fmac_f32_e32 v194, v60, v100
	v_add_f32_e32 v60, v190, v194
	v_lshlrev_b32_e32 v195, 16, v221
	v_mul_f32_e32 v60, v60, v195
	v_mul_f32_e32 v194, v105, v186
	v_fmac_f32_e32 v194, v61, v101
	v_add_f32_e32 v61, v190, v194
	v_and_b32_e32 v195, 0xffff0000, v221
	v_mul_f32_e32 v61, v61, v195
	v_cvt_pk_bf16_f32 v58, v58, v59
	v_cvt_pk_bf16_f32 v59, v60, v61
	global_store_dwordx2 v[176:177], v[58:59], off offset:1568
	v_mul_f32_e32 v194, v94, v186
	v_fmac_f32_e32 v194, v62, v90
	v_add_f32_e32 v62, v190, v194
	v_lshlrev_b32_e32 v195, 16, v222
	v_mul_f32_e32 v62, v62, v195
	v_mul_f32_e32 v194, v95, v186
	v_fmac_f32_e32 v194, v63, v91
	v_add_f32_e32 v63, v190, v194
	v_and_b32_e32 v195, 0xffff0000, v222
	v_mul_f32_e32 v63, v63, v195
	v_mul_f32_e32 v194, v96, v186
	v_fmac_f32_e32 v194, v64, v92
	v_add_f32_e32 v64, v190, v194
	v_lshlrev_b32_e32 v195, 16, v223
	v_mul_f32_e32 v64, v64, v195
	v_mul_f32_e32 v194, v97, v186
	v_fmac_f32_e32 v194, v65, v93
	v_add_f32_e32 v65, v190, v194
	v_and_b32_e32 v195, 0xffff0000, v223
	v_mul_f32_e32 v65, v65, v195
	v_cvt_pk_bf16_f32 v62, v62, v63
	v_cvt_pk_bf16_f32 v63, v64, v65
	global_store_dwordx2 v[176:177], v[62:63], off offset:1584
	v_mul_f32_e32 v194, v118, v187
	v_fmac_f32_e32 v194, v34, v114
	v_add_f32_e32 v34, v191, v194
	v_lshlrev_b32_e32 v195, 16, v224
	v_mul_f32_e32 v34, v34, v195
	v_mul_f32_e32 v194, v119, v187
	v_fmac_f32_e32 v194, v35, v115
	v_add_f32_e32 v35, v191, v194
	v_and_b32_e32 v195, 0xffff0000, v224
	v_mul_f32_e32 v35, v35, v195
	v_mul_f32_e32 v194, v120, v187
	v_fmac_f32_e32 v194, v36, v116
	v_add_f32_e32 v36, v191, v194
	v_lshlrev_b32_e32 v195, 16, v225
	v_mul_f32_e32 v36, v36, v195
	v_mul_f32_e32 v194, v121, v187
	v_fmac_f32_e32 v194, v37, v117
	v_add_f32_e32 v37, v191, v194
	v_and_b32_e32 v195, 0xffff0000, v225
	v_mul_f32_e32 v37, v37, v195
	v_cvt_pk_bf16_f32 v34, v34, v35
	v_cvt_pk_bf16_f32 v35, v36, v37
	global_store_dwordx2 v[178:179], v[34:35], off offset:1536
	v_mul_f32_e32 v194, v110, v187
	v_fmac_f32_e32 v194, v38, v106
	v_add_f32_e32 v38, v191, v194
	v_lshlrev_b32_e32 v195, 16, v226
	v_mul_f32_e32 v38, v38, v195
	v_mul_f32_e32 v194, v111, v187
	v_fmac_f32_e32 v194, v39, v107
	v_add_f32_e32 v39, v191, v194
	v_and_b32_e32 v195, 0xffff0000, v226
	v_mul_f32_e32 v39, v39, v195
	v_mul_f32_e32 v194, v112, v187
	v_fmac_f32_e32 v194, v40, v108
	v_add_f32_e32 v40, v191, v194
	v_lshlrev_b32_e32 v195, 16, v227
	v_mul_f32_e32 v40, v40, v195
	v_mul_f32_e32 v194, v113, v187
	v_fmac_f32_e32 v194, v41, v109
	v_add_f32_e32 v41, v191, v194
	v_and_b32_e32 v195, 0xffff0000, v227
	v_mul_f32_e32 v41, v41, v195
	v_cvt_pk_bf16_f32 v38, v38, v39
	v_cvt_pk_bf16_f32 v39, v40, v41
	global_store_dwordx2 v[178:179], v[38:39], off offset:1552
	v_mul_f32_e32 v194, v102, v187
	v_fmac_f32_e32 v194, v42, v98
	v_add_f32_e32 v42, v191, v194
	v_lshlrev_b32_e32 v195, 16, v228
	v_mul_f32_e32 v42, v42, v195
	v_mul_f32_e32 v194, v103, v187
	v_fmac_f32_e32 v194, v43, v99
	v_add_f32_e32 v43, v191, v194
	v_and_b32_e32 v195, 0xffff0000, v228
	v_mul_f32_e32 v43, v43, v195
	v_mul_f32_e32 v194, v104, v187
	v_fmac_f32_e32 v194, v44, v100
	v_add_f32_e32 v44, v191, v194
	v_lshlrev_b32_e32 v195, 16, v229
	v_mul_f32_e32 v44, v44, v195
	v_mul_f32_e32 v194, v105, v187
	v_fmac_f32_e32 v194, v45, v101
	v_add_f32_e32 v45, v191, v194
	v_and_b32_e32 v195, 0xffff0000, v229
	v_mul_f32_e32 v45, v45, v195
	v_cvt_pk_bf16_f32 v42, v42, v43
	v_cvt_pk_bf16_f32 v43, v44, v45
	global_store_dwordx2 v[178:179], v[42:43], off offset:1568
	v_mul_f32_e32 v194, v94, v187
	v_fmac_f32_e32 v194, v46, v90
	v_add_f32_e32 v46, v191, v194
	v_lshlrev_b32_e32 v195, 16, v230
	v_mul_f32_e32 v46, v46, v195
	v_mul_f32_e32 v194, v95, v187
	v_fmac_f32_e32 v194, v47, v91
	v_add_f32_e32 v47, v191, v194
	v_and_b32_e32 v195, 0xffff0000, v230
	v_mul_f32_e32 v47, v47, v195
	v_mul_f32_e32 v194, v96, v187
	v_fmac_f32_e32 v194, v48, v92
	v_add_f32_e32 v48, v191, v194
	v_lshlrev_b32_e32 v195, 16, v231
	v_mul_f32_e32 v48, v48, v195
	v_mul_f32_e32 v194, v97, v187
	v_fmac_f32_e32 v194, v49, v93
	v_add_f32_e32 v49, v191, v194
	v_and_b32_e32 v195, 0xffff0000, v231
	v_mul_f32_e32 v49, v49, v195
	v_cvt_pk_bf16_f32 v46, v46, v47
	v_cvt_pk_bf16_f32 v47, v48, v49
	global_store_dwordx2 v[178:179], v[46:47], off offset:1584
	v_mul_f32_e32 v194, v118, v188
	v_fmac_f32_e32 v194, v18, v114
	v_add_f32_e32 v18, v192, v194
	v_lshlrev_b32_e32 v195, 16, v232
	v_mul_f32_e32 v18, v18, v195
	v_mul_f32_e32 v194, v119, v188
	v_fmac_f32_e32 v194, v19, v115
	v_add_f32_e32 v19, v192, v194
	v_and_b32_e32 v195, 0xffff0000, v232
	v_mul_f32_e32 v19, v19, v195
	v_mul_f32_e32 v194, v120, v188
	v_fmac_f32_e32 v194, v20, v116
	v_add_f32_e32 v20, v192, v194
	v_lshlrev_b32_e32 v195, 16, v233
	v_mul_f32_e32 v20, v20, v195
	v_mul_f32_e32 v194, v121, v188
	v_fmac_f32_e32 v194, v21, v117
	v_add_f32_e32 v21, v192, v194
	v_and_b32_e32 v195, 0xffff0000, v233
	v_mul_f32_e32 v21, v21, v195
	v_cvt_pk_bf16_f32 v18, v18, v19
	v_cvt_pk_bf16_f32 v19, v20, v21
	global_store_dwordx2 v[182:183], v[18:19], off offset:1536
	v_mul_f32_e32 v194, v110, v188
	v_fmac_f32_e32 v194, v22, v106
	v_add_f32_e32 v22, v192, v194
	v_lshlrev_b32_e32 v195, 16, v234
	v_mul_f32_e32 v22, v22, v195
	v_mul_f32_e32 v194, v111, v188
	v_fmac_f32_e32 v194, v23, v107
	v_add_f32_e32 v23, v192, v194
	v_and_b32_e32 v195, 0xffff0000, v234
	v_mul_f32_e32 v23, v23, v195
	v_mul_f32_e32 v194, v112, v188
	v_fmac_f32_e32 v194, v24, v108
	v_add_f32_e32 v24, v192, v194
	v_lshlrev_b32_e32 v195, 16, v235
	v_mul_f32_e32 v24, v24, v195
	v_mul_f32_e32 v194, v113, v188
	v_fmac_f32_e32 v194, v25, v109
	v_add_f32_e32 v25, v192, v194
	v_and_b32_e32 v195, 0xffff0000, v235
	v_mul_f32_e32 v25, v25, v195
	v_cvt_pk_bf16_f32 v22, v22, v23
	v_cvt_pk_bf16_f32 v23, v24, v25
	global_store_dwordx2 v[182:183], v[22:23], off offset:1552
	v_mul_f32_e32 v194, v102, v188
	v_fmac_f32_e32 v194, v26, v98
	v_add_f32_e32 v26, v192, v194
	v_lshlrev_b32_e32 v195, 16, v236
	v_mul_f32_e32 v26, v26, v195
	v_mul_f32_e32 v194, v103, v188
	v_fmac_f32_e32 v194, v27, v99
	v_add_f32_e32 v27, v192, v194
	v_and_b32_e32 v195, 0xffff0000, v236
	v_mul_f32_e32 v27, v27, v195
	v_mul_f32_e32 v194, v104, v188
	v_fmac_f32_e32 v194, v28, v100
	v_add_f32_e32 v28, v192, v194
	v_lshlrev_b32_e32 v195, 16, v237
	v_mul_f32_e32 v28, v28, v195
	v_mul_f32_e32 v194, v105, v188
	v_fmac_f32_e32 v194, v29, v101
	v_add_f32_e32 v29, v192, v194
	v_and_b32_e32 v195, 0xffff0000, v237
	v_mul_f32_e32 v29, v29, v195
	v_cvt_pk_bf16_f32 v26, v26, v27
	v_cvt_pk_bf16_f32 v27, v28, v29
	global_store_dwordx2 v[182:183], v[26:27], off offset:1568
	v_mul_f32_e32 v194, v94, v188
	v_fmac_f32_e32 v194, v30, v90
	v_add_f32_e32 v30, v192, v194
	v_lshlrev_b32_e32 v195, 16, v238
	v_mul_f32_e32 v30, v30, v195
	v_mul_f32_e32 v194, v95, v188
	v_fmac_f32_e32 v194, v31, v91
	v_add_f32_e32 v31, v192, v194
	v_and_b32_e32 v195, 0xffff0000, v238
	v_mul_f32_e32 v31, v31, v195
	v_mul_f32_e32 v194, v96, v188
	v_fmac_f32_e32 v194, v32, v92
	v_add_f32_e32 v32, v192, v194
	v_lshlrev_b32_e32 v195, 16, v239
	v_mul_f32_e32 v32, v32, v195
	v_mul_f32_e32 v194, v97, v188
	v_fmac_f32_e32 v194, v33, v93
	v_add_f32_e32 v33, v192, v194
	v_and_b32_e32 v195, 0xffff0000, v239
	v_mul_f32_e32 v33, v33, v195
	v_cvt_pk_bf16_f32 v30, v30, v31
	v_cvt_pk_bf16_f32 v31, v32, v33
	global_store_dwordx2 v[182:183], v[30:31], off offset:1584
	v_mul_f32_e32 v194, v118, v189
	v_fmac_f32_e32 v194, v2, v114
	v_add_f32_e32 v2, v193, v194
	v_lshlrev_b32_e32 v195, 16, v240
	v_mul_f32_e32 v2, v2, v195
	v_mul_f32_e32 v194, v119, v189
	v_fmac_f32_e32 v194, v3, v115
	v_add_f32_e32 v3, v193, v194
	v_and_b32_e32 v195, 0xffff0000, v240
	v_mul_f32_e32 v3, v3, v195
	v_mul_f32_e32 v194, v120, v189
	v_fmac_f32_e32 v194, v4, v116
	v_add_f32_e32 v4, v193, v194
	v_lshlrev_b32_e32 v195, 16, v241
	v_mul_f32_e32 v4, v4, v195
	v_mul_f32_e32 v194, v121, v189
	v_fmac_f32_e32 v194, v5, v117
	v_add_f32_e32 v5, v193, v194
	v_and_b32_e32 v195, 0xffff0000, v241
	v_mul_f32_e32 v5, v5, v195
	v_cvt_pk_bf16_f32 v2, v2, v3
	v_cvt_pk_bf16_f32 v3, v4, v5
	global_store_dwordx2 v[184:185], v[2:3], off offset:1536
	v_mul_f32_e32 v194, v110, v189
	v_fmac_f32_e32 v194, v6, v106
	v_add_f32_e32 v6, v193, v194
	v_lshlrev_b32_e32 v195, 16, v246
	v_mul_f32_e32 v6, v6, v195
	v_mul_f32_e32 v194, v111, v189
	v_fmac_f32_e32 v194, v7, v107
	v_add_f32_e32 v7, v193, v194
	v_and_b32_e32 v195, 0xffff0000, v246
	v_mul_f32_e32 v7, v7, v195
	v_mul_f32_e32 v194, v112, v189
	v_fmac_f32_e32 v194, v8, v108
	v_add_f32_e32 v8, v193, v194
	v_lshlrev_b32_e32 v195, 16, v247
	v_mul_f32_e32 v8, v8, v195
	v_mul_f32_e32 v194, v113, v189
	v_fmac_f32_e32 v194, v9, v109
	v_add_f32_e32 v9, v193, v194
	v_and_b32_e32 v195, 0xffff0000, v247
	v_mul_f32_e32 v9, v9, v195
	v_cvt_pk_bf16_f32 v6, v6, v7
	v_cvt_pk_bf16_f32 v7, v8, v9
	global_store_dwordx2 v[184:185], v[6:7], off offset:1552
	v_mul_f32_e32 v194, v102, v189
	v_fmac_f32_e32 v194, v10, v98
	v_add_f32_e32 v10, v193, v194
	v_lshlrev_b32_e32 v195, 16, v252
	v_mul_f32_e32 v10, v10, v195
	v_mul_f32_e32 v194, v103, v189
	v_fmac_f32_e32 v194, v11, v99
	v_add_f32_e32 v11, v193, v194
	v_and_b32_e32 v195, 0xffff0000, v252
	v_mul_f32_e32 v11, v11, v195
	v_mul_f32_e32 v194, v104, v189
	v_fmac_f32_e32 v194, v12, v100
	v_add_f32_e32 v12, v193, v194
	v_lshlrev_b32_e32 v195, 16, v253
	v_mul_f32_e32 v12, v12, v195
	v_mul_f32_e32 v194, v105, v189
	v_fmac_f32_e32 v194, v13, v101
	v_add_f32_e32 v13, v193, v194
	v_and_b32_e32 v195, 0xffff0000, v253
	v_mul_f32_e32 v13, v13, v195
	v_cvt_pk_bf16_f32 v10, v10, v11
	v_cvt_pk_bf16_f32 v11, v12, v13
	global_store_dwordx2 v[184:185], v[10:11], off offset:1568
	v_mul_f32_e32 v194, v94, v189
	v_fmac_f32_e32 v194, v14, v90
	v_add_f32_e32 v14, v193, v194
	v_lshlrev_b32_e32 v195, 16, v254
	v_mul_f32_e32 v14, v14, v195
	v_mul_f32_e32 v194, v95, v189
	v_fmac_f32_e32 v194, v15, v91
	v_add_f32_e32 v15, v193, v194
	v_and_b32_e32 v195, 0xffff0000, v254
	v_mul_f32_e32 v15, v15, v195
	v_mul_f32_e32 v194, v96, v189
	v_fmac_f32_e32 v194, v16, v92
	v_add_f32_e32 v16, v193, v194
	v_lshlrev_b32_e32 v195, 16, v255
	v_mul_f32_e32 v16, v16, v195
	v_mul_f32_e32 v194, v97, v189
	v_fmac_f32_e32 v194, v17, v93
	v_add_f32_e32 v17, v193, v194
	v_and_b32_e32 v195, 0xffff0000, v255
	v_mul_f32_e32 v17, v17, v195
	v_cvt_pk_bf16_f32 v14, v14, v15
	v_cvt_pk_bf16_f32 v15, v16, v17
	global_store_dwordx2 v[184:185], v[14:15], off offset:1584
	s_barrier
	s_cbranch_scc0 .LBB0_779

.LBB0_849:
	v_mov_b32_e32 v43, v0
	s_ashr_i32 s5, s3, 31
	v_ashrrev_i32_e32 v44, 7, v43
	s_waitcnt vmcnt(7)
	v_add_u32_e32 v130, s2, v44
	v_ashrrev_i32_e32 v131, 31, v130
	v_and_b32_e32 v134, 31, v43
	s_waitcnt vmcnt(0)
	v_lshlrev_b64 v[2:3], 15, v[130:131]
	v_bfe_u32 v135, v43, 5, 1
	v_lshl_add_u64 v[2:3], s[56:57], 0, v[2:3]
	v_lshlrev_b32_e32 v154, 8, v134
	v_lshl_add_u64 v[2:3], v[2:3], 0, v[154:155]
	v_lshlrev_b32_e32 v154, 4, v135
	v_ashrrev_i32_e32 v45, 2, v43
	v_add_u32_e32 v18, s3, v45
	v_ashrrev_i32_e32 v19, 31, v18
	v_lshlrev_b32_e32 v20, 6, v43
	v_lshlrev_b64 v[18:19], 12, v[18:19]
	v_and_b32_e32 v46, 0xc0, v20
	v_lshl_add_u64 v[18:19], s[60:61], 0, v[18:19]
	v_lshlrev_b32_e32 v20, 1, v46
	v_mov_b32_e32 v21, v155
	v_lshl_add_u64 v[34:35], v[18:19], 0, v[20:21]
	global_load_dwordx4 v[18:21], v[34:35], off offset:3632
	global_load_dwordx4 v[22:25], v[34:35], off offset:3616
	global_load_dwordx4 v[26:29], v[34:35], off offset:3600
	global_load_dwordx4 v[30:33], v[34:35], off offset:3584
	global_load_dwordx4 v[36:39], v[34:35], off offset:3680
	global_load_dwordx4 v[176:179], v[34:35], off offset:3664
	global_load_dwordx4 v[48:51], v[34:35], off offset:3648
	global_load_dwordx4 v[182:185], v[34:35], off offset:3696
	v_lshl_add_u64 v[52:53], v[2:3], 0, v[154:155]
	v_add_co_u32_e32 v54, vcc, s14, v52
	s_nop 0
	v_addc_co_u32_e32 v55, vcc, 0, v53, vcc
	v_add_co_u32_e32 v56, vcc, s17, v52
	global_load_dwordx4 v[2:5], v[52:53], off
	global_load_dwordx4 v[6:9], v[54:55], off
	v_addc_co_u32_e32 v57, vcc, 0, v53, vcc
	v_add_co_u32_e32 v58, vcc, s30, v52
	global_load_dwordx4 v[10:13], v[56:57], off
	s_nop 0
	v_addc_co_u32_e32 v59, vcc, 0, v53, vcc
	global_load_dwordx4 v[14:17], v[58:59], off
	global_load_dwordx4 v[114:117], v[52:53], off offset:32
	global_load_dwordx4 v[118:121], v[54:55], off offset:32
	global_load_dwordx4 v[122:125], v[56:57], off offset:32
	global_load_dwordx4 v[126:129], v[58:59], off offset:32
	global_load_dwordx4 v[102:105], v[54:55], off offset:64
	global_load_dwordx4 v[106:109], v[56:57], off offset:64
	global_load_dwordx4 v[110:113], v[58:59], off offset:64
	global_load_dwordx4 v[90:93], v[54:55], off offset:96
	global_load_dwordx4 v[94:97], v[56:57], off offset:96
	global_load_dwordx4 v[98:101], v[58:59], off offset:96
	global_load_dwordx4 v[82:85], v[56:57], off offset:128
	global_load_dwordx4 v[86:89], v[58:59], off offset:128
	global_load_dwordx4 v[74:77], v[56:57], off offset:160
	global_load_dwordx4 v[78:81], v[58:59], off offset:160
	global_load_dwordx4 v[70:73], v[58:59], off offset:192
	global_load_dwordx4 v[66:69], v[58:59], off offset:224
	v_and_b32_e32 v215, 31, v0
	v_add_u32_e32 v215, s3, v215
	v_lshlrev_b32_e32 v215, 12, v215
	v_and_b32_e32 v245, 0x1c0, v0
	v_add_u32_e32 v215, v215, v245
	v_bfe_u32 v245, v0, 5, 1
	v_lshl_add_u32 v215, v245, 3, v215
	global_load_dwordx2 v[216:217], v215, s[60:61] offset:3072
	global_load_dwordx2 v[218:219], v215, s[60:61] offset:3088
	global_load_dwordx2 v[220:221], v215, s[60:61] offset:3104
	global_load_dwordx2 v[222:223], v215, s[60:61] offset:3120
	s_add_u32 s98, s60, 0x20000
	s_addc_u32 s99, s61, 0
	global_load_dwordx2 v[224:225], v215, s[98:99] offset:3072
	global_load_dwordx2 v[226:227], v215, s[98:99] offset:3088
	global_load_dwordx2 v[228:229], v215, s[98:99] offset:3104
	global_load_dwordx2 v[230:231], v215, s[98:99] offset:3120
	s_add_u32 s100, s60, 0x40000
	s_addc_u32 s101, s61, 0
	global_load_dwordx2 v[232:233], v215, s[100:101] offset:3072
	global_load_dwordx2 v[234:235], v215, s[100:101] offset:3088
	global_load_dwordx2 v[236:237], v215, s[100:101] offset:3104
	global_load_dwordx2 v[238:239], v215, s[100:101] offset:3120
	s_add_u32 s98, s60, 0x60000
	s_addc_u32 s99, s61, 0
	global_load_dwordx2 v[240:241], v215, s[98:99] offset:3072
	global_load_dwordx2 v[246:247], v215, s[98:99] offset:3088
	global_load_dwordx2 v[252:253], v215, s[98:99] offset:3104
	global_load_dwordx2 v[254:255], v215, s[98:99] offset:3120
	v_lshrrev_b32_e32 v42, 5, v43
	s_add_i32 s4, s4, s46
	s_waitcnt vmcnt(43)
	v_lshlrev_b32_e32 v144, 16, v18
	s_waitcnt vmcnt(42)
	v_lshlrev_b32_e32 v150, 16, v22
	s_waitcnt vmcnt(41)
	v_lshlrev_b32_e32 v168, 16, v26
	s_waitcnt vmcnt(40)
	v_lshlrev_b32_e32 v174, 16, v30
	v_and_b32_e32 v173, 0xffff0000, v30
	v_add_f32_e32 v30, 0, v174
	v_lshlrev_b32_e32 v172, 16, v31
	v_add_f32_e32 v30, v30, v173
	v_and_b32_e32 v171, 0xffff0000, v31
	v_mul_f32_e32 v31, v173, v173
	v_add_f32_e32 v30, v30, v172
	v_lshlrev_b32_e32 v170, 16, v32
	v_fmac_f32_e32 v31, v174, v174
	v_add_f32_e32 v30, v30, v171
	v_and_b32_e32 v169, 0xffff0000, v32
	v_fmac_f32_e32 v31, v172, v172
	v_add_f32_e32 v30, v30, v170
	v_lshlrev_b32_e32 v167, 16, v33
	v_fmac_f32_e32 v31, v171, v171
	v_add_f32_e32 v30, v30, v169
	v_and_b32_e32 v165, 0xffff0000, v33
	v_fmac_f32_e32 v31, v170, v170
	v_add_f32_e32 v30, v30, v167
	v_fmac_f32_e32 v31, v169, v169
	v_add_f32_e32 v30, v30, v165
	v_fmac_f32_e32 v31, v167, v167
	v_and_b32_e32 v166, 0xffff0000, v26
	v_add_f32_e32 v26, v30, v168
	v_fmac_f32_e32 v31, v165, v165
	v_lshlrev_b32_e32 v164, 16, v27
	v_add_f32_e32 v26, v26, v166
	v_and_b32_e32 v153, 0xffff0000, v27
	v_fmac_f32_e32 v31, v168, v168
	v_add_f32_e32 v26, v26, v164
	v_lshlrev_b32_e32 v152, 16, v28
	v_fmac_f32_e32 v31, v166, v166
	v_add_f32_e32 v26, v26, v153
	v_and_b32_e32 v151, 0xffff0000, v28
	v_fmac_f32_e32 v31, v164, v164
	v_add_f32_e32 v26, v26, v152
	v_lshlrev_b32_e32 v148, 16, v29
	v_fmac_f32_e32 v31, v153, v153
	v_add_f32_e32 v26, v26, v151
	v_and_b32_e32 v146, 0xffff0000, v29
	v_fmac_f32_e32 v31, v152, v152
	v_add_f32_e32 v26, v26, v148
	v_fmac_f32_e32 v31, v151, v151
	v_add_f32_e32 v26, v26, v146
	v_fmac_f32_e32 v31, v148, v148
	v_and_b32_e32 v149, 0xffff0000, v22
	v_add_f32_e32 v22, v26, v150
	v_fmac_f32_e32 v31, v146, v146
	v_lshlrev_b32_e32 v147, 16, v23
	v_add_f32_e32 v22, v22, v149
	v_and_b32_e32 v145, 0xffff0000, v23
	v_fmac_f32_e32 v31, v150, v150
	v_add_f32_e32 v22, v22, v147
	v_lshlrev_b32_e32 v143, 16, v24
	v_fmac_f32_e32 v31, v149, v149
	v_add_f32_e32 v22, v22, v145
	v_and_b32_e32 v141, 0xffff0000, v24
	v_fmac_f32_e32 v31, v147, v147
	v_add_f32_e32 v22, v22, v143
	v_lshlrev_b32_e32 v139, 16, v25
	v_fmac_f32_e32 v31, v145, v145
	v_add_f32_e32 v22, v22, v141
	v_and_b32_e32 v137, 0xffff0000, v25
	v_fmac_f32_e32 v31, v143, v143
	v_add_f32_e32 v22, v22, v139
	v_fmac_f32_e32 v31, v141, v141
	v_add_f32_e32 v22, v22, v137
	v_fmac_f32_e32 v31, v139, v139
	v_and_b32_e32 v142, 0xffff0000, v18
	v_add_f32_e32 v18, v22, v144
	v_fmac_f32_e32 v31, v137, v137
	v_lshlrev_b32_e32 v140, 16, v19
	v_add_f32_e32 v18, v18, v142
	v_and_b32_e32 v138, 0xffff0000, v19
	v_fmac_f32_e32 v31, v144, v144
	v_add_f32_e32 v18, v18, v140
	v_lshlrev_b32_e32 v133, 16, v20
	v_fmac_f32_e32 v31, v142, v142
	v_add_f32_e32 v18, v18, v138
	v_and_b32_e32 v131, 0xffff0000, v20
	v_fmac_f32_e32 v31, v140, v140
	v_add_f32_e32 v18, v18, v133
	v_lshlrev_b32_e32 v64, 16, v21
	v_fmac_f32_e32 v31, v138, v138
	v_add_f32_e32 v18, v18, v131
	v_and_b32_e32 v62, 0xffff0000, v21
	v_fmac_f32_e32 v31, v133, v133
	v_add_f32_e32 v18, v18, v64
	v_fmac_f32_e32 v31, v131, v131
	v_add_f32_e32 v18, v18, v62
	s_waitcnt vmcnt(37)
	v_lshlrev_b32_e32 v136, 16, v48
	v_fmac_f32_e32 v31, v64, v64
	v_and_b32_e32 v132, 0xffff0000, v48
	v_add_f32_e32 v18, v18, v136
	v_fmac_f32_e32 v31, v62, v62
	v_lshlrev_b32_e32 v65, 16, v49
	v_add_f32_e32 v18, v18, v132
	v_and_b32_e32 v63, 0xffff0000, v49
	v_fmac_f32_e32 v31, v136, v136
	v_add_f32_e32 v18, v18, v65
	v_lshlrev_b32_e32 v60, 16, v50
	v_fmac_f32_e32 v31, v132, v132
	v_add_f32_e32 v18, v18, v63
	v_and_b32_e32 v59, 0xffff0000, v50
	v_fmac_f32_e32 v31, v65, v65
	v_add_f32_e32 v18, v18, v60
	v_lshlrev_b32_e32 v57, 16, v51
	v_fmac_f32_e32 v31, v63, v63
	v_add_f32_e32 v18, v18, v59
	v_and_b32_e32 v55, 0xffff0000, v51
	v_fmac_f32_e32 v31, v60, v60
	v_add_f32_e32 v18, v18, v57
	v_fmac_f32_e32 v31, v59, v59
	v_add_f32_e32 v18, v18, v55
	v_lshlrev_b32_e32 v61, 16, v176
	v_fmac_f32_e32 v31, v57, v57
	v_and_b32_e32 v58, 0xffff0000, v176
	v_add_f32_e32 v18, v18, v61
	v_fmac_f32_e32 v31, v55, v55
	v_lshlrev_b32_e32 v56, 16, v177
	v_add_f32_e32 v18, v18, v58
	v_and_b32_e32 v54, 0xffff0000, v177
	v_fmac_f32_e32 v31, v61, v61
	v_add_f32_e32 v18, v18, v56
	v_lshlrev_b32_e32 v53, 16, v178
	v_fmac_f32_e32 v31, v58, v58
	v_add_f32_e32 v18, v18, v54
	v_and_b32_e32 v51, 0xffff0000, v178
	v_fmac_f32_e32 v31, v56, v56
	v_add_f32_e32 v18, v18, v53
	v_lshlrev_b32_e32 v49, 16, v179
	v_fmac_f32_e32 v31, v54, v54
	v_add_f32_e32 v18, v18, v51
	v_and_b32_e32 v47, 0xffff0000, v179
	v_fmac_f32_e32 v31, v53, v53
	v_add_f32_e32 v18, v18, v49
	v_fmac_f32_e32 v31, v51, v51
	v_add_f32_e32 v18, v18, v47
	v_lshlrev_b32_e32 v52, 16, v36
	v_fmac_f32_e32 v31, v49, v49
	v_and_b32_e32 v50, 0xffff0000, v36
	v_add_f32_e32 v18, v18, v52
	v_fmac_f32_e32 v31, v47, v47
	v_lshlrev_b32_e32 v48, 16, v37
	v_add_f32_e32 v18, v18, v50
	v_fmac_f32_e32 v31, v52, v52
	v_add_f32_e32 v18, v18, v48
	v_and_b32_e32 v37, 0xffff0000, v37
	v_fmac_f32_e32 v31, v50, v50
	v_lshlrev_b32_e32 v34, 16, v38
	v_mov_b32_e32 v35, v37
	v_add_f32_e32 v20, v18, v37
	v_fmac_f32_e32 v31, v48, v48
	v_and_b32_e32 v24, 0xffff0000, v38
	v_pk_mul_f32 v[18:19], v[34:35], v[34:35]
	v_add_f32_e32 v20, v20, v34
	v_lshlrev_b32_e32 v25, 16, v39
	v_add_f32_e32 v19, v19, v31
	v_add_f32_e32 v20, v20, v24
	v_add_f32_e32 v21, v18, v19
	v_pk_mul_f32 v[18:19], v[24:25], v[24:25]
	v_add_f32_e32 v20, v20, v25
	v_and_b32_e32 v33, 0xffff0000, v39
	v_add_f32_e32 v18, v18, v21
	s_waitcnt vmcnt(36)
	v_lshlrev_b32_e32 v28, 16, v182
	v_mov_b32_e32 v29, v33
	v_add_f32_e32 v20, v20, v33
	v_add_f32_e32 v21, v19, v18
	v_and_b32_e32 v22, 0xffff0000, v182
	v_pk_mul_f32 v[18:19], v[28:29], v[28:29]
	v_add_f32_e32 v20, v20, v28
	v_lshlrev_b32_e32 v23, 16, v183
	v_add_f32_e32 v19, v19, v21
	v_add_f32_e32 v20, v20, v22
	v_add_f32_e32 v21, v18, v19
	v_pk_mul_f32 v[18:19], v[22:23], v[22:23]
	v_add_f32_e32 v29, v20, v23
	v_and_b32_e32 v31, 0xffff0000, v183
	v_add_f32_e32 v18, v18, v21
	v_lshlrev_b32_e32 v26, 16, v184
	v_mov_b32_e32 v27, v31
	v_add_f32_e32 v29, v29, v31
	v_and_b32_e32 v36, s0, v38
	v_add_f32_e32 v18, v19, v18
	v_and_b32_e32 v20, 0xffff0000, v184
	v_pk_mul_f32 v[38:39], v[26:27], v[26:27]
	v_add_f32_e32 v27, v29, v26
	v_lshlrev_b32_e32 v21, 16, v185
	v_add_f32_e32 v18, v39, v18
	v_add_f32_e32 v27, v27, v20
	v_and_b32_e32 v29, 64, v181
	v_add_f32_e32 v18, v38, v18
	v_pk_mul_f32 v[40:41], v[20:21], v[20:21]
	v_add_f32_e32 v39, v27, v21
	v_xor_b32_e32 v27, 1, v181
	v_add_u32_e32 v29, 64, v29
	v_and_b32_e32 v19, 0xffff0000, v185
	v_add_f32_e32 v18, v40, v18
	v_cmp_lt_i32_e32 vcc, v27, v29
	v_add_f32_e32 v18, v41, v18
	v_mul_f32_e32 v38, v19, v19
	v_cndmask_b32_e32 v27, v181, v27, vcc
	v_lshlrev_b32_e32 v27, 2, v27
	v_pk_add_f32 v[38:39], v[38:39], v[18:19]
	ds_bpermute_b32 v41, v27, v39
	ds_bpermute_b32 v40, v27, v38
	v_xor_b32_e32 v35, 2, v181
	v_cmp_lt_i32_e32 vcc, v35, v29
	v_and_b32_e32 v30, s0, v182
	v_mov_b32_e32 v32, v36
	v_cndmask_b32_e32 v29, v181, v35, vcc
	v_lshlrev_b32_e32 v29, 2, v29
	s_waitcnt lgkmcnt(0)
	v_pk_add_f32 v[38:39], v[38:39], v[40:41]
	ds_bpermute_b32 v41, v29, v39
	ds_bpermute_b32 v40, v29, v38
	s_waitcnt lgkmcnt(0)
	v_pk_add_f32 v[40:41], v[38:39], v[40:41]
	s_nop 0
	v_pk_mul_f32 v[38:39], v[40:41], s[22:23] op_sel_hi:[1,0]
	v_pk_fma_f32 v[36:37], v[40:41], s[22:23], v[36:37] op_sel_hi:[1,0,1] neg_lo:[1,0,0] neg_hi:[1,0,0]
	v_fma_f32 v18, -v39, v39, v38
	v_max_f32_e32 v18, 0, v18
	v_add_f32_e32 v18, 0x358637bd, v18
	v_cmp_gt_f32_e32 vcc, s33, v18
	v_mul_f32_e32 v27, 0x4b800000, v18
	v_sub_f32_e32 v29, v174, v39
	v_cndmask_b32_e32 v18, v18, v27, vcc
	v_rsq_f32_e32 v18, v18
	v_sub_f32_e32 v19, v19, v39
	v_mul_f32_e32 v27, 0x45800000, v18
	v_cndmask_b32_e32 v18, v18, v27, vcc
	v_mul_f32_e32 v29, v29, v18
	v_lshlrev_b32_e32 v27, 1, v45
	v_bfe_u32 v35, v29, 16, 1
	v_ashrrev_i32_e32 v45, 1, v43
	v_and_b32_e32 v27, 14, v27
	v_add3_u32 v29, v29, v35, s15
	v_lshl_add_u32 v35, v46, 8, 32
	v_and_b32_e32 v46, -16, v45
	v_add3_u32 v174, v35, v46, v27
	ds_write_b16_d16_hi v174, v29 offset:55296
	v_mul_f32_e64 v215, -v39, v18
	v_fma_f32 v29, v173, v18, v215
	v_cvt_pk_bf16_f32 v29, v29, v29
	v_bitop3_b32 v173, v45, 16, -16 bitop3:0x6c
	v_add3_u32 v175, v35, v173, v27
	ds_write_b16 v175, v29 offset:55552
	v_fma_f32 v29, v172, v18, v215
	v_cvt_pk_bf16_f32 v29, v29, v29
	v_bitop3_b32 v172, v45, 32, -16 bitop3:0x6c
	v_add3_u32 v176, v35, v172, v27
	ds_write_b16 v176, v29 offset:55808
	v_fma_f32 v29, v171, v18, v215
	v_cvt_pk_bf16_f32 v29, v29, v29
	v_bitop3_b32 v171, v45, 48, -16 bitop3:0x6c
	v_add3_u32 v177, v35, v171, v27
	ds_write_b16 v177, v29 offset:56064
	v_fma_f32 v29, v170, v18, v215
	v_cvt_pk_bf16_f32 v29, v29, v29
	v_bitop3_b32 v170, v45, 64, -16 bitop3:0x6c
	v_add3_u32 v178, v35, v170, v27
	ds_write_b16 v178, v29 offset:56320
	v_fma_f32 v29, v169, v18, v215
	v_cvt_pk_bf16_f32 v29, v29, v29
	v_bitop3_b32 v169, v45, s34, -16 bitop3:0x6c
	v_add3_u32 v179, v35, v169, v27
	ds_write_b16 v179, v29 offset:56576
	v_fma_f32 v29, v167, v18, v215
	v_cvt_pk_bf16_f32 v29, v29, v29
	v_bitop3_b32 v167, v45, s31, -16 bitop3:0x6c
	v_add3_u32 v182, v35, v167, v27
	ds_write_b16 v182, v29 offset:56832
	v_fma_f32 v29, v165, v18, v215
	v_cvt_pk_bf16_f32 v29, v29, v29
	v_bitop3_b32 v165, v45, s13, -16 bitop3:0x6c
	v_add3_u32 v183, v35, v165, v27
	ds_write_b16 v183, v29 offset:57088
	v_fma_f32 v29, v168, v18, v215
	v_cvt_pk_bf16_f32 v29, v29, v29
	v_bitop3_b32 v168, v45, s12, -16 bitop3:0x6c
	v_add3_u32 v184, v35, v168, v27
	ds_write_b16 v184, v29 offset:57344
	v_fma_f32 v29, v166, v18, v215
	v_cvt_pk_bf16_f32 v29, v29, v29
	v_bitop3_b32 v166, v45, s35, -16 bitop3:0x6c
	v_add3_u32 v185, v35, v166, v27
	ds_write_b16 v185, v29 offset:57600
	v_fma_f32 v29, v164, v18, v215
	v_cvt_pk_bf16_f32 v29, v29, v29
	v_bitop3_b32 v164, v45, s38, -16 bitop3:0x6c
	v_add3_u32 v186, v35, v164, v27
	ds_write_b16 v186, v29 offset:57856
	v_fma_f32 v29, v153, v18, v215
	v_cvt_pk_bf16_f32 v29, v29, v29
	v_bitop3_b32 v153, v45, s39, -16 bitop3:0x6c
	v_add3_u32 v187, v35, v153, v27
	ds_write_b16 v187, v29 offset:58112
	v_fma_f32 v29, v152, v18, v215
	v_cvt_pk_bf16_f32 v29, v29, v29
	v_bitop3_b32 v152, v45, s16, -16 bitop3:0x6c
	v_add3_u32 v188, v35, v152, v27
	ds_write_b16 v188, v29 offset:58368
	v_fma_f32 v29, v151, v18, v215
	v_cvt_pk_bf16_f32 v29, v29, v29
	v_bitop3_b32 v151, v45, s40, -16 bitop3:0x6c
	v_add3_u32 v189, v35, v151, v27
	ds_write_b16 v189, v29 offset:58624
	v_fma_f32 v29, v148, v18, v215
	v_cvt_pk_bf16_f32 v29, v29, v29
	v_bitop3_b32 v148, v45, s41, -16 bitop3:0x6c
	v_add3_u32 v190, v35, v148, v27
	ds_write_b16 v190, v29 offset:58880
	v_sub_f32_e32 v29, v146, v39
	v_mul_f32_e32 v29, v29, v18
	v_bfe_u32 v146, v29, 16, 1
	v_bitop3_b32 v45, v45, s42, -16 bitop3:0x6c
	v_add_u32_e32 v38, 0xd800, v35
	v_add3_u32 v29, v29, v146, s15
	v_add3_u32 v35, v35, v45, v27
	ds_write_b16_d16_hi v35, v29 offset:59136
	v_fma_f32 v29, v150, v18, v215
	v_cvt_pk_bf16_f32 v29, v29, v29
	ds_write_b16 v174, v29 offset:59392
	v_fma_f32 v29, v149, v18, v215
	v_cvt_pk_bf16_f32 v29, v29, v29
	ds_write_b16 v175, v29 offset:59648
	v_fma_f32 v29, v147, v18, v215
	v_cvt_pk_bf16_f32 v29, v29, v29
	ds_write_b16 v176, v29 offset:59904
	v_fma_f32 v29, v145, v18, v215
	v_cvt_pk_bf16_f32 v29, v29, v29
	ds_write_b16 v177, v29 offset:60160
	v_fma_f32 v29, v143, v18, v215
	v_cvt_pk_bf16_f32 v29, v29, v29
	ds_write_b16 v178, v29 offset:60416
	v_fma_f32 v29, v141, v18, v215
	v_cvt_pk_bf16_f32 v29, v29, v29
	ds_write_b16 v179, v29 offset:60672
	v_fma_f32 v29, v139, v18, v215
	v_cvt_pk_bf16_f32 v29, v29, v29
	ds_write_b16 v182, v29 offset:60928
	v_fma_f32 v29, v137, v18, v215
	v_cvt_pk_bf16_f32 v29, v29, v29
	ds_write_b16 v183, v29 offset:61184
	v_fma_f32 v29, v144, v18, v215
	v_cvt_pk_bf16_f32 v29, v29, v29
	ds_write_b16 v184, v29 offset:61440
	v_fma_f32 v29, v142, v18, v215
	v_cvt_pk_bf16_f32 v29, v29, v29
	ds_write_b16 v185, v29 offset:61696
	v_fma_f32 v29, v140, v18, v215
	v_cvt_pk_bf16_f32 v29, v29, v29
	ds_write_b16 v186, v29 offset:61952
	v_fma_f32 v29, v138, v18, v215
	v_cvt_pk_bf16_f32 v29, v29, v29
	ds_write_b16 v187, v29 offset:62208
	v_fma_f32 v29, v133, v18, v215
	v_cvt_pk_bf16_f32 v29, v29, v29
	ds_write_b16 v188, v29 offset:62464
	v_fma_f32 v29, v131, v18, v215
	v_cvt_pk_bf16_f32 v29, v29, v29
	ds_write_b16 v189, v29 offset:62720
	v_fma_f32 v29, v64, v18, v215
	v_cvt_pk_bf16_f32 v29, v29, v29
	ds_write_b16 v190, v29 offset:62976
	v_fma_f32 v29, v62, v18, v215
	v_cvt_pk_bf16_f32 v29, v29, v29
	ds_write_b16 v35, v29 offset:63232
	v_fma_f32 v29, v136, v18, v215
	v_cvt_pk_bf16_f32 v29, v29, v29
	ds_write_b16 v174, v29 offset:63488
	v_fma_f32 v29, v132, v18, v215
	v_cvt_pk_bf16_f32 v29, v29, v29
	ds_write_b16 v175, v29 offset:63744
	v_fma_f32 v29, v65, v18, v215
	v_cvt_pk_bf16_f32 v29, v29, v29
	ds_write_b16 v176, v29 offset:64000
	v_fma_f32 v29, v63, v18, v215
	v_cvt_pk_bf16_f32 v29, v29, v29
	ds_write_b16 v177, v29 offset:64256
	v_fma_f32 v29, v60, v18, v215
	v_cvt_pk_bf16_f32 v29, v29, v29
	ds_write_b16 v178, v29 offset:64512
	v_fma_f32 v29, v59, v18, v215
	v_cvt_pk_bf16_f32 v29, v29, v29
	ds_write_b16 v179, v29 offset:64768
	v_fma_f32 v29, v57, v18, v215
	v_cvt_pk_bf16_f32 v29, v29, v29
	ds_write_b16 v182, v29 offset:65024
	v_fma_f32 v29, v55, v18, v215
	v_cvt_pk_bf16_f32 v29, v29, v29
	ds_write_b16 v183, v29 offset:65280
	v_fma_f32 v29, v61, v18, v215
	v_cvt_pk_bf16_f32 v29, v29, v29
	v_add3_u32 v35, v38, v168, v27
	ds_write_b16 v35, v29 offset:10240
	v_fma_f32 v29, v58, v18, v215
	v_cvt_pk_bf16_f32 v29, v29, v29
	v_add3_u32 v55, v38, v166, v27
	ds_write_b16 v55, v29 offset:10496
	v_fma_f32 v29, v56, v18, v215
	v_cvt_pk_bf16_f32 v29, v29, v29
	v_add3_u32 v56, v38, v164, v27
	ds_write_b16 v56, v29 offset:10752
	v_fma_f32 v29, v54, v18, v215
	v_cvt_pk_bf16_f32 v29, v29, v29
	v_add3_u32 v54, v38, v153, v27
	ds_write_b16 v54, v29 offset:11008
	v_fma_f32 v29, v53, v18, v215
	v_cvt_pk_bf16_f32 v29, v29, v29
	v_add3_u32 v53, v38, v152, v27
	ds_write_b16 v53, v29 offset:11264
	v_fma_f32 v29, v51, v18, v215
	v_cvt_pk_bf16_f32 v29, v29, v29
	v_add3_u32 v51, v38, v151, v27
	ds_write_b16 v51, v29 offset:11520
	v_fma_f32 v29, v49, v18, v215
	v_cvt_pk_bf16_f32 v29, v29, v29
	v_add3_u32 v49, v38, v148, v27
	ds_write_b16 v49, v29 offset:11776
	v_fma_f32 v29, v47, v18, v215
	v_cvt_pk_bf16_f32 v29, v29, v29
	v_add3_u32 v45, v38, v45, v27
	ds_write_b16 v45, v29 offset:12032
	v_fma_f32 v29, v52, v18, v215
	v_cvt_pk_bf16_f32 v29, v29, v29
	v_add3_u32 v46, v38, v46, v27
	ds_write_b16 v46, v29 offset:12288
	v_fma_f32 v29, v50, v18, v215
	v_cvt_pk_bf16_f32 v29, v29, v29
	v_add3_u32 v46, v38, v173, v27
	ds_write_b16 v46, v29 offset:12544
	v_fma_f32 v29, v48, v18, v215
	v_cvt_pk_bf16_f32 v29, v29, v29
	v_add3_u32 v46, v38, v172, v27
	ds_write_b16 v46, v29 offset:12800
	v_mul_f32_e32 v29, v37, v18
	v_bfe_u32 v36, v29, 16, 1
	v_add3_u32 v29, v29, v36, s15
	v_add3_u32 v36, v38, v171, v27
	ds_write_b16_d16_hi v36, v29 offset:13056
	v_fma_f32 v29, v34, v18, v215
	v_cvt_pk_bf16_f32 v29, v29, v29
	v_add3_u32 v34, v38, v170, v27
	ds_write_b16 v34, v29 offset:13312
	v_sub_f32_e32 v29, v24, v39
	v_pk_fma_f32 v[24:25], v[40:41], s[22:23], v[24:25] op_sel_hi:[1,0,1] neg_lo:[1,0,0] neg_hi:[1,0,0]
	v_mul_f32_e32 v29, v29, v18
	v_mul_f32_e32 v24, v25, v18
	v_bfe_u32 v34, v29, 16, 1
	v_bfe_u32 v25, v24, 16, 1
	v_add3_u32 v29, v29, v34, s15
	v_add3_u32 v34, v38, v169, v27
	v_add3_u32 v24, v24, v25, s15
	v_add3_u32 v25, v38, v167, v27
	ds_write_b16_d16_hi v34, v29 offset:13568
	ds_write_b16_d16_hi v25, v24 offset:13824
	v_pk_fma_f32 v[24:25], v[40:41], s[22:23], v[32:33] op_sel_hi:[1,0,1] neg_lo:[1,0,0] neg_hi:[1,0,0]
	v_and_b32_e32 v133, 15, v43
	v_mul_f32_e32 v24, v25, v18
	v_bfe_u32 v25, v24, 16, 1
	v_add3_u32 v24, v24, v25, s15
	v_add3_u32 v25, v38, v165, v27
	ds_write_b16_d16_hi v25, v24 offset:14080
	v_fma_f32 v24, v28, v18, v215
	v_cvt_pk_bf16_f32 v24, v24, v24
	ds_write_b16 v35, v24 offset:14336
	v_sub_f32_e32 v24, v22, v39
	v_pk_fma_f32 v[22:23], v[40:41], s[22:23], v[22:23] op_sel_hi:[1,0,1] neg_lo:[1,0,0] neg_hi:[1,0,0]
	v_mul_f32_e32 v24, v24, v18
	v_mul_f32_e32 v22, v23, v18
	v_bfe_u32 v25, v24, 16, 1
	v_bfe_u32 v23, v22, 16, 1
	v_add3_u32 v24, v24, v25, s15
	v_add3_u32 v22, v22, v23, s15
	ds_write_b16_d16_hi v55, v24 offset:14592
	ds_write_b16_d16_hi v56, v22 offset:14848
	v_pk_fma_f32 v[22:23], v[40:41], s[22:23], v[30:31] op_sel_hi:[1,0,1] neg_lo:[1,0,0] neg_hi:[1,0,0]
	s_nop 0
	v_mul_f32_e32 v22, v23, v18
	v_bfe_u32 v23, v22, 16, 1
	v_add3_u32 v22, v22, v23, s15
	ds_write_b16_d16_hi v54, v22 offset:15104
	v_fma_f32 v22, v26, v18, v215
	v_cvt_pk_bf16_f32 v22, v22, v22
	ds_write_b16 v53, v22 offset:15360
	v_sub_f32_e32 v22, v20, v39
	v_pk_fma_f32 v[20:21], v[40:41], s[22:23], v[20:21] op_sel_hi:[1,0,1] neg_lo:[1,0,0] neg_hi:[1,0,0]
	v_mul_f32_e32 v22, v22, v18
	v_mul_f32_e32 v20, v21, v18
	v_mul_f32_e32 v18, v19, v18
	v_bfe_u32 v23, v22, 16, 1
	v_bfe_u32 v21, v20, 16, 1
	v_bfe_u32 v19, v18, 16, 1
	v_add3_u32 v22, v22, v23, s15
	v_add3_u32 v20, v20, v21, s15
	v_add3_u32 v18, v18, v19, s15
	ds_write_b16_d16_hi v51, v22 offset:15616
	ds_write_b16_d16_hi v49, v20 offset:15872
	ds_write_b16_d16_hi v45, v18 offset:16128
	v_lshrrev_b32_e32 v18, 1, v43
	v_and_b32_e32 v18, 32, v18
	v_lshl_or_b32 v132, v44, 6, v18
	v_or_b32_e32 v18, v132, v134
	v_lshl_add_u32 v131, v18, 8, 32
	v_bitop3_b32 v18, v42, v133, 1 bitop3:0x6c
	v_lshl_add_u32 v18, v18, 4, v131
	s_waitcnt lgkmcnt(0)
	s_waitcnt vmcnt(16)
	s_barrier
	ds_read_b128 v[136:139], v18 offset:55296
	s_waitcnt lgkmcnt(0)
	v_mfma_f32_32x32x16_bf16 v[50:65], v[136:139], v[2:5], 0
	v_mfma_f32_32x32x16_bf16 v[34:49], v[136:139], v[6:9], 0
	v_mfma_f32_32x32x16_bf16 v[18:33], v[136:139], v[10:13], 0
	v_mfma_f32_32x32x16_bf16 v[2:17], v[136:139], v[14:17], 0
	v_bitop3_b32 v136, v135, v133, 2 bitop3:0x36
	v_lshl_add_u32 v136, v136, 4, v131
	ds_read_b128 v[136:139], v136 offset:55296
	s_waitcnt lgkmcnt(0)
	v_mfma_f32_32x32x16_bf16 v[50:65], v[136:139], v[114:117], v[50:65]
	v_bitop3_b32 v114, v135, v133, 4 bitop3:0x36
	v_lshl_add_u32 v114, v114, 4, v131
	ds_read_b128 v[114:117], v114 offset:55296
	v_mfma_f32_32x32x16_bf16 v[34:49], v[136:139], v[118:121], v[34:49]
	v_mfma_f32_32x32x16_bf16 v[18:33], v[136:139], v[122:125], v[18:33]
	s_waitcnt lgkmcnt(0)
	v_mfma_f32_32x32x16_bf16 v[34:49], v[114:117], v[102:105], v[34:49]
	v_bitop3_b32 v102, v135, v133, 6 bitop3:0x36
	v_lshl_add_u32 v102, v102, 4, v131
	ds_read_b128 v[102:105], v102 offset:55296
	v_mfma_f32_32x32x16_bf16 v[2:17], v[136:139], v[126:129], v[2:17]
	v_mfma_f32_32x32x16_bf16 v[18:33], v[114:117], v[106:109], v[18:33]
	s_waitcnt lgkmcnt(0)
	v_mfma_f32_32x32x16_bf16 v[34:49], v[102:105], v[90:93], v[34:49]
	v_bitop3_b32 v90, v135, v133, 8 bitop3:0x36
	v_lshl_add_u32 v90, v90, 4, v131
	ds_read_b128 v[90:93], v90 offset:55296
	v_mfma_f32_32x32x16_bf16 v[2:17], v[114:117], v[110:113], v[2:17]
	v_mfma_f32_32x32x16_bf16 v[18:33], v[102:105], v[94:97], v[18:33]
	v_mfma_f32_32x32x16_bf16 v[2:17], v[102:105], v[98:101], v[2:17]
	v_lshlrev_b32_e32 v104, 7, v130
	v_or_b32_e32 v102, v104, v134
	v_ashrrev_i32_e32 v103, 31, v102
	v_lshlrev_b64 v[106:107], 2, v[102:103]
	v_lshl_or_b32 v98, v135, 2, v132
	v_or_b32_e32 v100, s3, v134
	v_mov_b32_e32 v101, s5
	s_waitcnt lgkmcnt(0)
	v_mfma_f32_32x32x16_bf16 v[18:33], v[90:93], v[82:85], v[18:33]
	v_bitop3_b32 v82, v135, v133, 10 bitop3:0x36
	v_lshl_add_u32 v82, v82, 4, v131
	ds_read_b128 v[82:85], v82 offset:55296
	v_lshl_add_u64 v[108:109], s[6:7], 0, v[106:107]
	v_lshl_add_u64 v[106:107], s[92:93], 0, v[106:107]
	v_ashrrev_i32_e32 v99, 31, v98
	v_lshlrev_b64 v[98:99], 1, v[98:99]
	v_mfma_f32_32x32x16_bf16 v[2:17], v[90:93], v[86:89], v[2:17]
	s_add_i32 s3, s3, s18
	s_cmpk_gt_i32 s4, 0x7f
	s_waitcnt lgkmcnt(0)
	v_mfma_f32_32x32x16_bf16 v[18:33], v[82:85], v[74:77], v[18:33]
	v_bitop3_b32 v74, v135, v133, 12 bitop3:0x36
	v_lshl_add_u32 v74, v74, 4, v131
	ds_read_b128 v[74:77], v74 offset:55296
	v_mfma_f32_32x32x16_bf16 v[2:17], v[82:85], v[78:81], v[2:17]
	s_waitcnt lgkmcnt(0)
	v_mfma_f32_32x32x16_bf16 v[2:17], v[74:77], v[70:73], v[2:17]
	v_bitop3_b32 v70, v135, v133, 14 bitop3:0x36
	v_lshl_add_u32 v70, v70, 4, v131
	ds_read_b128 v[70:73], v70 offset:55296
	v_ashrrev_i32_e32 v133, 31, v132
	s_waitcnt lgkmcnt(0)
	v_mfma_f32_32x32x16_bf16 v[2:17], v[70:73], v[66:69], v[2:17]
	v_lshlrev_b64 v[66:67], 2, v[132:133]
	v_lshl_add_u64 v[68:69], s[10:11], 0, v[66:67]
	v_lshl_add_u64 v[66:67], s[36:37], 0, v[66:67]
	v_lshl_add_u64 v[68:69], v[68:69], 0, v[154:155]
	v_lshl_add_u64 v[70:71], v[66:67], 0, v[154:155]
	global_load_dwordx4 v[90:93], v[68:69], off
	global_load_dwordx4 v[94:97], v[70:71], off
	global_load_dwordx4 v[82:85], v[68:69], off offset:32
	global_load_dwordx4 v[86:89], v[70:71], off offset:32
	global_load_dwordx4 v[74:77], v[68:69], off offset:64
	global_load_dwordx4 v[78:81], v[70:71], off offset:64
	s_nop 0
	global_load_dwordx4 v[66:69], v[68:69], off offset:96
	s_nop 0
	global_load_dwordx4 v[70:73], v[70:71], off offset:96
	s_nop 0
	global_load_dword v150, v[108:109], off
	global_load_dword v151, v[108:109], off offset:128
	global_load_dword v152, v[108:109], off offset:256
	global_load_dword v153, v[108:109], off offset:384
	global_load_dword v164, v[106:107], off
	global_load_dword v165, v[106:107], off offset:128
	global_load_dword v166, v[106:107], off offset:256
	global_load_dword v167, v[106:107], off offset:384
	v_lshlrev_b64 v[142:143], 11, v[100:101]
	v_lshl_add_u64 v[142:143], s[62:63], 0, v[142:143]
	v_lshl_add_u64 v[142:143], v[142:143], 0, v[98:99]
	v_add_co_u32_e32 v144, vcc, 0x10000, v142
	s_nop 1
	v_addc_co_u32_e32 v145, vcc, 0, v143, vcc
	v_add_co_u32_e32 v146, vcc, 0x20000, v142
	s_nop 1
	v_addc_co_u32_e32 v147, vcc, 0, v143, vcc
	v_add_co_u32_e32 v148, vcc, 0x30000, v142
	s_nop 1
	v_addc_co_u32_e32 v149, vcc, 0, v143, vcc
	s_waitcnt vmcnt(0)
	v_mul_f32_e32 v168, v94, v150
	v_fmac_f32_e32 v168, v50, v90
	v_add_f32_e32 v50, v164, v168
	v_lshlrev_b32_e32 v169, 16, v216
	v_mul_f32_e32 v50, v50, v169
	v_mul_f32_e32 v168, v95, v150
	v_fmac_f32_e32 v168, v51, v91
	v_add_f32_e32 v51, v164, v168
	v_and_b32_e32 v169, 0xffff0000, v216
	v_mul_f32_e32 v51, v51, v169
	v_mul_f32_e32 v168, v96, v150
	v_fmac_f32_e32 v168, v52, v92
	v_add_f32_e32 v52, v164, v168
	v_lshlrev_b32_e32 v169, 16, v217
	v_mul_f32_e32 v52, v52, v169
	v_mul_f32_e32 v168, v97, v150
	v_fmac_f32_e32 v168, v53, v93
	v_add_f32_e32 v53, v164, v168
	v_and_b32_e32 v169, 0xffff0000, v217
	v_mul_f32_e32 v53, v53, v169
	v_cvt_pk_bf16_f32 v50, v50, v51
	v_cvt_pk_bf16_f32 v51, v52, v53
	global_store_dwordx2 v[142:143], v[50:51], off offset:1536
	v_mul_f32_e32 v168, v86, v150
	v_fmac_f32_e32 v168, v54, v82
	v_add_f32_e32 v54, v164, v168
	v_lshlrev_b32_e32 v169, 16, v218
	v_mul_f32_e32 v54, v54, v169
	v_mul_f32_e32 v168, v87, v150
	v_fmac_f32_e32 v168, v55, v83
	v_add_f32_e32 v55, v164, v168
	v_and_b32_e32 v169, 0xffff0000, v218
	v_mul_f32_e32 v55, v55, v169
	v_mul_f32_e32 v168, v88, v150
	v_fmac_f32_e32 v168, v56, v84
	v_add_f32_e32 v56, v164, v168
	v_lshlrev_b32_e32 v169, 16, v219
	v_mul_f32_e32 v56, v56, v169
	v_mul_f32_e32 v168, v89, v150
	v_fmac_f32_e32 v168, v57, v85
	v_add_f32_e32 v57, v164, v168
	v_and_b32_e32 v169, 0xffff0000, v219
	v_mul_f32_e32 v57, v57, v169
	v_cvt_pk_bf16_f32 v54, v54, v55
	v_cvt_pk_bf16_f32 v55, v56, v57
	global_store_dwordx2 v[142:143], v[54:55], off offset:1552
	v_mul_f32_e32 v168, v78, v150
	v_fmac_f32_e32 v168, v58, v74
	v_add_f32_e32 v58, v164, v168
	v_lshlrev_b32_e32 v169, 16, v220
	v_mul_f32_e32 v58, v58, v169
	v_mul_f32_e32 v168, v79, v150
	v_fmac_f32_e32 v168, v59, v75
	v_add_f32_e32 v59, v164, v168
	v_and_b32_e32 v169, 0xffff0000, v220
	v_mul_f32_e32 v59, v59, v169
	v_mul_f32_e32 v168, v80, v150
	v_fmac_f32_e32 v168, v60, v76
	v_add_f32_e32 v60, v164, v168
	v_lshlrev_b32_e32 v169, 16, v221
	v_mul_f32_e32 v60, v60, v169
	v_mul_f32_e32 v168, v81, v150
	v_fmac_f32_e32 v168, v61, v77
	v_add_f32_e32 v61, v164, v168
	v_and_b32_e32 v169, 0xffff0000, v221
	v_mul_f32_e32 v61, v61, v169
	v_cvt_pk_bf16_f32 v58, v58, v59
	v_cvt_pk_bf16_f32 v59, v60, v61
	global_store_dwordx2 v[142:143], v[58:59], off offset:1568
	v_mul_f32_e32 v168, v70, v150
	v_fmac_f32_e32 v168, v62, v66
	v_add_f32_e32 v62, v164, v168
	v_lshlrev_b32_e32 v169, 16, v222
	v_mul_f32_e32 v62, v62, v169
	v_mul_f32_e32 v168, v71, v150
	v_fmac_f32_e32 v168, v63, v67
	v_add_f32_e32 v63, v164, v168
	v_and_b32_e32 v169, 0xffff0000, v222
	v_mul_f32_e32 v63, v63, v169
	v_mul_f32_e32 v168, v72, v150
	v_fmac_f32_e32 v168, v64, v68
	v_add_f32_e32 v64, v164, v168
	v_lshlrev_b32_e32 v169, 16, v223
	v_mul_f32_e32 v64, v64, v169
	v_mul_f32_e32 v168, v73, v150
	v_fmac_f32_e32 v168, v65, v69
	v_add_f32_e32 v65, v164, v168
	v_and_b32_e32 v169, 0xffff0000, v223
	v_mul_f32_e32 v65, v65, v169
	v_cvt_pk_bf16_f32 v62, v62, v63
	v_cvt_pk_bf16_f32 v63, v64, v65
	global_store_dwordx2 v[142:143], v[62:63], off offset:1584
	v_mul_f32_e32 v168, v94, v151
	v_fmac_f32_e32 v168, v34, v90
	v_add_f32_e32 v34, v165, v168
	v_lshlrev_b32_e32 v169, 16, v224
	v_mul_f32_e32 v34, v34, v169
	v_mul_f32_e32 v168, v95, v151
	v_fmac_f32_e32 v168, v35, v91
	v_add_f32_e32 v35, v165, v168
	v_and_b32_e32 v169, 0xffff0000, v224
	v_mul_f32_e32 v35, v35, v169
	v_mul_f32_e32 v168, v96, v151
	v_fmac_f32_e32 v168, v36, v92
	v_add_f32_e32 v36, v165, v168
	v_lshlrev_b32_e32 v169, 16, v225
	v_mul_f32_e32 v36, v36, v169
	v_mul_f32_e32 v168, v97, v151
	v_fmac_f32_e32 v168, v37, v93
	v_add_f32_e32 v37, v165, v168
	v_and_b32_e32 v169, 0xffff0000, v225
	v_mul_f32_e32 v37, v37, v169
	v_cvt_pk_bf16_f32 v34, v34, v35
	v_cvt_pk_bf16_f32 v35, v36, v37
	global_store_dwordx2 v[144:145], v[34:35], off offset:1536
	v_mul_f32_e32 v168, v86, v151
	v_fmac_f32_e32 v168, v38, v82
	v_add_f32_e32 v38, v165, v168
	v_lshlrev_b32_e32 v169, 16, v226
	v_mul_f32_e32 v38, v38, v169
	v_mul_f32_e32 v168, v87, v151
	v_fmac_f32_e32 v168, v39, v83
	v_add_f32_e32 v39, v165, v168
	v_and_b32_e32 v169, 0xffff0000, v226
	v_mul_f32_e32 v39, v39, v169
	v_mul_f32_e32 v168, v88, v151
	v_fmac_f32_e32 v168, v40, v84
	v_add_f32_e32 v40, v165, v168
	v_lshlrev_b32_e32 v169, 16, v227
	v_mul_f32_e32 v40, v40, v169
	v_mul_f32_e32 v168, v89, v151
	v_fmac_f32_e32 v168, v41, v85
	v_add_f32_e32 v41, v165, v168
	v_and_b32_e32 v169, 0xffff0000, v227
	v_mul_f32_e32 v41, v41, v169
	v_cvt_pk_bf16_f32 v38, v38, v39
	v_cvt_pk_bf16_f32 v39, v40, v41
	global_store_dwordx2 v[144:145], v[38:39], off offset:1552
	v_mul_f32_e32 v168, v78, v151
	v_fmac_f32_e32 v168, v42, v74
	v_add_f32_e32 v42, v165, v168
	v_lshlrev_b32_e32 v169, 16, v228
	v_mul_f32_e32 v42, v42, v169
	v_mul_f32_e32 v168, v79, v151
	v_fmac_f32_e32 v168, v43, v75
	v_add_f32_e32 v43, v165, v168
	v_and_b32_e32 v169, 0xffff0000, v228
	v_mul_f32_e32 v43, v43, v169
	v_mul_f32_e32 v168, v80, v151
	v_fmac_f32_e32 v168, v44, v76
	v_add_f32_e32 v44, v165, v168
	v_lshlrev_b32_e32 v169, 16, v229
	v_mul_f32_e32 v44, v44, v169
	v_mul_f32_e32 v168, v81, v151
	v_fmac_f32_e32 v168, v45, v77
	v_add_f32_e32 v45, v165, v168
	v_and_b32_e32 v169, 0xffff0000, v229
	v_mul_f32_e32 v45, v45, v169
	v_cvt_pk_bf16_f32 v42, v42, v43
	v_cvt_pk_bf16_f32 v43, v44, v45
	global_store_dwordx2 v[144:145], v[42:43], off offset:1568
	v_mul_f32_e32 v168, v70, v151
	v_fmac_f32_e32 v168, v46, v66
	v_add_f32_e32 v46, v165, v168
	v_lshlrev_b32_e32 v169, 16, v230
	v_mul_f32_e32 v46, v46, v169
	v_mul_f32_e32 v168, v71, v151
	v_fmac_f32_e32 v168, v47, v67
	v_add_f32_e32 v47, v165, v168
	v_and_b32_e32 v169, 0xffff0000, v230
	v_mul_f32_e32 v47, v47, v169
	v_mul_f32_e32 v168, v72, v151
	v_fmac_f32_e32 v168, v48, v68
	v_add_f32_e32 v48, v165, v168
	v_lshlrev_b32_e32 v169, 16, v231
	v_mul_f32_e32 v48, v48, v169
	v_mul_f32_e32 v168, v73, v151
	v_fmac_f32_e32 v168, v49, v69
	v_add_f32_e32 v49, v165, v168
	v_and_b32_e32 v169, 0xffff0000, v231
	v_mul_f32_e32 v49, v49, v169
	v_cvt_pk_bf16_f32 v46, v46, v47
	v_cvt_pk_bf16_f32 v47, v48, v49
	global_store_dwordx2 v[144:145], v[46:47], off offset:1584
	v_mul_f32_e32 v168, v94, v152
	v_fmac_f32_e32 v168, v18, v90
	v_add_f32_e32 v18, v166, v168
	v_lshlrev_b32_e32 v169, 16, v232
	v_mul_f32_e32 v18, v18, v169
	v_mul_f32_e32 v168, v95, v152
	v_fmac_f32_e32 v168, v19, v91
	v_add_f32_e32 v19, v166, v168
	v_and_b32_e32 v169, 0xffff0000, v232
	v_mul_f32_e32 v19, v19, v169
	v_mul_f32_e32 v168, v96, v152
	v_fmac_f32_e32 v168, v20, v92
	v_add_f32_e32 v20, v166, v168
	v_lshlrev_b32_e32 v169, 16, v233
	v_mul_f32_e32 v20, v20, v169
	v_mul_f32_e32 v168, v97, v152
	v_fmac_f32_e32 v168, v21, v93
	v_add_f32_e32 v21, v166, v168
	v_and_b32_e32 v169, 0xffff0000, v233
	v_mul_f32_e32 v21, v21, v169
	v_cvt_pk_bf16_f32 v18, v18, v19
	v_cvt_pk_bf16_f32 v19, v20, v21
	global_store_dwordx2 v[146:147], v[18:19], off offset:1536
	v_mul_f32_e32 v168, v86, v152
	v_fmac_f32_e32 v168, v22, v82
	v_add_f32_e32 v22, v166, v168
	v_lshlrev_b32_e32 v169, 16, v234
	v_mul_f32_e32 v22, v22, v169
	v_mul_f32_e32 v168, v87, v152
	v_fmac_f32_e32 v168, v23, v83
	v_add_f32_e32 v23, v166, v168
	v_and_b32_e32 v169, 0xffff0000, v234
	v_mul_f32_e32 v23, v23, v169
	v_mul_f32_e32 v168, v88, v152
	v_fmac_f32_e32 v168, v24, v84
	v_add_f32_e32 v24, v166, v168
	v_lshlrev_b32_e32 v169, 16, v235
	v_mul_f32_e32 v24, v24, v169
	v_mul_f32_e32 v168, v89, v152
	v_fmac_f32_e32 v168, v25, v85
	v_add_f32_e32 v25, v166, v168
	v_and_b32_e32 v169, 0xffff0000, v235
	v_mul_f32_e32 v25, v25, v169
	v_cvt_pk_bf16_f32 v22, v22, v23
	v_cvt_pk_bf16_f32 v23, v24, v25
	global_store_dwordx2 v[146:147], v[22:23], off offset:1552
	v_mul_f32_e32 v168, v78, v152
	v_fmac_f32_e32 v168, v26, v74
	v_add_f32_e32 v26, v166, v168
	v_lshlrev_b32_e32 v169, 16, v236
	v_mul_f32_e32 v26, v26, v169
	v_mul_f32_e32 v168, v79, v152
	v_fmac_f32_e32 v168, v27, v75
	v_add_f32_e32 v27, v166, v168
	v_and_b32_e32 v169, 0xffff0000, v236
	v_mul_f32_e32 v27, v27, v169
	v_mul_f32_e32 v168, v80, v152
	v_fmac_f32_e32 v168, v28, v76
	v_add_f32_e32 v28, v166, v168
	v_lshlrev_b32_e32 v169, 16, v237
	v_mul_f32_e32 v28, v28, v169
	v_mul_f32_e32 v168, v81, v152
	v_fmac_f32_e32 v168, v29, v77
	v_add_f32_e32 v29, v166, v168
	v_and_b32_e32 v169, 0xffff0000, v237
	v_mul_f32_e32 v29, v29, v169
	v_cvt_pk_bf16_f32 v26, v26, v27
	v_cvt_pk_bf16_f32 v27, v28, v29
	global_store_dwordx2 v[146:147], v[26:27], off offset:1568
	v_mul_f32_e32 v168, v70, v152
	v_fmac_f32_e32 v168, v30, v66
	v_add_f32_e32 v30, v166, v168
	v_lshlrev_b32_e32 v169, 16, v238
	v_mul_f32_e32 v30, v30, v169
	v_mul_f32_e32 v168, v71, v152
	v_fmac_f32_e32 v168, v31, v67
	v_add_f32_e32 v31, v166, v168
	v_and_b32_e32 v169, 0xffff0000, v238
	v_mul_f32_e32 v31, v31, v169
	v_mul_f32_e32 v168, v72, v152
	v_fmac_f32_e32 v168, v32, v68
	v_add_f32_e32 v32, v166, v168
	v_lshlrev_b32_e32 v169, 16, v239
	v_mul_f32_e32 v32, v32, v169
	v_mul_f32_e32 v168, v73, v152
	v_fmac_f32_e32 v168, v33, v69
	v_add_f32_e32 v33, v166, v168
	v_and_b32_e32 v169, 0xffff0000, v239
	v_mul_f32_e32 v33, v33, v169
	v_cvt_pk_bf16_f32 v30, v30, v31
	v_cvt_pk_bf16_f32 v31, v32, v33
	global_store_dwordx2 v[146:147], v[30:31], off offset:1584
	v_mul_f32_e32 v168, v94, v153
	v_fmac_f32_e32 v168, v2, v90
	v_add_f32_e32 v2, v167, v168
	v_lshlrev_b32_e32 v169, 16, v240
	v_mul_f32_e32 v2, v2, v169
	v_mul_f32_e32 v168, v95, v153
	v_fmac_f32_e32 v168, v3, v91
	v_add_f32_e32 v3, v167, v168
	v_and_b32_e32 v169, 0xffff0000, v240
	v_mul_f32_e32 v3, v3, v169
	v_mul_f32_e32 v168, v96, v153
	v_fmac_f32_e32 v168, v4, v92
	v_add_f32_e32 v4, v167, v168
	v_lshlrev_b32_e32 v169, 16, v241
	v_mul_f32_e32 v4, v4, v169
	v_mul_f32_e32 v168, v97, v153
	v_fmac_f32_e32 v168, v5, v93
	v_add_f32_e32 v5, v167, v168
	v_and_b32_e32 v169, 0xffff0000, v241
	v_mul_f32_e32 v5, v5, v169
	v_cvt_pk_bf16_f32 v2, v2, v3
	v_cvt_pk_bf16_f32 v3, v4, v5
	global_store_dwordx2 v[148:149], v[2:3], off offset:1536
	v_mul_f32_e32 v168, v86, v153
	v_fmac_f32_e32 v168, v6, v82
	v_add_f32_e32 v6, v167, v168
	v_lshlrev_b32_e32 v169, 16, v246
	v_mul_f32_e32 v6, v6, v169
	v_mul_f32_e32 v168, v87, v153
	v_fmac_f32_e32 v168, v7, v83
	v_add_f32_e32 v7, v167, v168
	v_and_b32_e32 v169, 0xffff0000, v246
	v_mul_f32_e32 v7, v7, v169
	v_mul_f32_e32 v168, v88, v153
	v_fmac_f32_e32 v168, v8, v84
	v_add_f32_e32 v8, v167, v168
	v_lshlrev_b32_e32 v169, 16, v247
	v_mul_f32_e32 v8, v8, v169
	v_mul_f32_e32 v168, v89, v153
	v_fmac_f32_e32 v168, v9, v85
	v_add_f32_e32 v9, v167, v168
	v_and_b32_e32 v169, 0xffff0000, v247
	v_mul_f32_e32 v9, v9, v169
	v_cvt_pk_bf16_f32 v6, v6, v7
	v_cvt_pk_bf16_f32 v7, v8, v9
	global_store_dwordx2 v[148:149], v[6:7], off offset:1552
	v_mul_f32_e32 v168, v78, v153
	v_fmac_f32_e32 v168, v10, v74
	v_add_f32_e32 v10, v167, v168
	v_lshlrev_b32_e32 v169, 16, v252
	v_mul_f32_e32 v10, v10, v169
	v_mul_f32_e32 v168, v79, v153
	v_fmac_f32_e32 v168, v11, v75
	v_add_f32_e32 v11, v167, v168
	v_and_b32_e32 v169, 0xffff0000, v252
	v_mul_f32_e32 v11, v11, v169
	v_mul_f32_e32 v168, v80, v153
	v_fmac_f32_e32 v168, v12, v76
	v_add_f32_e32 v12, v167, v168
	v_lshlrev_b32_e32 v169, 16, v253
	v_mul_f32_e32 v12, v12, v169
	v_mul_f32_e32 v168, v81, v153
	v_fmac_f32_e32 v168, v13, v77
	v_add_f32_e32 v13, v167, v168
	v_and_b32_e32 v169, 0xffff0000, v253
	v_mul_f32_e32 v13, v13, v169
	v_cvt_pk_bf16_f32 v10, v10, v11
	v_cvt_pk_bf16_f32 v11, v12, v13
	global_store_dwordx2 v[148:149], v[10:11], off offset:1568
	v_mul_f32_e32 v168, v70, v153
	v_fmac_f32_e32 v168, v14, v66
	v_add_f32_e32 v14, v167, v168
	v_lshlrev_b32_e32 v169, 16, v254
	v_mul_f32_e32 v14, v14, v169
	v_mul_f32_e32 v168, v71, v153
	v_fmac_f32_e32 v168, v15, v67
	v_add_f32_e32 v15, v167, v168
	v_and_b32_e32 v169, 0xffff0000, v254
	v_mul_f32_e32 v15, v15, v169
	v_mul_f32_e32 v168, v72, v153
	v_fmac_f32_e32 v168, v16, v68
	v_add_f32_e32 v16, v167, v168
	v_lshlrev_b32_e32 v169, 16, v255
	v_mul_f32_e32 v16, v16, v169
	v_mul_f32_e32 v168, v73, v153
	v_fmac_f32_e32 v168, v17, v69
	v_add_f32_e32 v17, v167, v168
	v_and_b32_e32 v169, 0xffff0000, v255
	v_mul_f32_e32 v17, v17, v169
	v_cvt_pk_bf16_f32 v14, v14, v15
	v_cvt_pk_bf16_f32 v15, v16, v17
	global_store_dwordx2 v[148:149], v[14:15], off offset:1584
	s_barrier
	s_cbranch_scc0 .LBB0_849
